# prep gate pass: dot product regrouped to natural lr pairs (10 fewer VALU per row), dead log fixups removed; scan k^T direct; later phases padded back to baseline code addresses
# baseline (speedup 1.0000x reference)
; #define LAS __attribute__((address_space(3)))
; __device__ __forceinline__ void gla_prep_phase(const Ctx& c, int j, LAS unsigned char* lds) {
;     ...
;         float up[16];
; #pragma unroll
;         for (int r = 0; r < 16; ++r) up[r] = pup[r];
;         const float bias = pbias;
;         { const int un = u + c.G; have = un < 2 * 16 * NCH; if (have) PREP_FETCH(un); }
;         __syncthreads();
;         float run = 0.f;
; #pragma unroll 4
;         for (int ii = 0; ii < 32; ++ii) { const int i = half * 32 + ii; float z = bias;
; #pragma unroll
;             for (int r = 0; r < 16; r += 4) { const f32x4 l4 = *(const LAS f32x4*)(LR + i * 16 + r); z += l4.x * up[r] + l4.y * up[r + 1] + l4.z * up[r + 2] + l4.w * up[r + 3]; }
;             const float ls = fminf(z, 0.f) - __logf(1.f + __expf(-fabsf(z)));
;             const bool valid = (ch > 0) || (i >= 48);
;             run += valid ? ls * (1.f / 16.f) : 0.f; CUM[i * 256 + d] = run; }
.LBB0_672:
	s_cmp_gt_i32 s12, 0
	s_mov_b32 s0, 0
	v_mov_b32_e32 v152, 0
	s_cselect_b64 s[96:97], -1, 0
	v_mov_b32_e32 v150, v135
	v_mov_b32_e32 v151, v134
	v_mov_b32_e32 v202, v2
	v_mov_b32_e32 v203, v0
	v_mov_b32_e32 v204, v4
	v_mov_b32_e32 v205, v6
	v_mov_b32_e32 v206, v3
	v_mov_b32_e32 v207, v1
	v_mov_b32_e32 v208, v5
	v_mov_b32_e32 v209, v7
	v_mov_b32_e32 v210, v10
	v_mov_b32_e32 v211, v8
	v_mov_b32_e32 v212, v12
	v_mov_b32_e32 v213, v14
	v_mov_b32_e32 v214, v11
	v_mov_b32_e32 v215, v9
	v_mov_b32_e32 v216, v13
	v_mov_b32_e32 v217, v15
	s_waitcnt lgkmcnt(0)
	s_barrier
.LBB0_673:
	v_add_u32_e32 v173, 0, v150
	ds_read_b128 v[154:157], v173
	ds_read_b128 v[158:161], v173 offset:16
	ds_read_b128 v[162:165], v173 offset:32
	ds_read_b128 v[166:169], v173 offset:48
	v_add_u32_e32 v172, s0, v53
	v_add_u32_e32 v171, 0, v151
	v_add_u32_e32 v174, 2, v172
	s_add_i32 s0, s0, 4
	s_waitcnt lgkmcnt(0)
	v_pk_mul_f32 v[218:219], v[202:203], v[154:155]
	v_pk_mul_f32 v[220:221], v[210:211], v[162:163]
	v_pk_fma_f32 v[218:219], v[204:205], v[156:157], v[218:219]
	v_pk_fma_f32 v[220:221], v[212:213], v[164:165], v[220:221]
	v_pk_fma_f32 v[218:219], v[206:207], v[158:159], v[218:219]
	v_pk_fma_f32 v[220:221], v[214:215], v[166:167], v[220:221]
	v_pk_fma_f32 v[218:219], v[208:209], v[160:161], v[218:219]
	v_pk_fma_f32 v[220:221], v[216:217], v[168:169], v[220:221]
	s_nop 0
	v_pk_add_f32 v[218:219], v[218:219], v[220:221]
	s_nop 0
	v_add_f32_e32 v153, v105, v218
	v_add_f32_e32 v153, v153, v219
	v_min_f32_e32 v154, 0, v153
	v_mul_f32_e64 v153, |v153|, s6
	v_exp_f32_e32 v153, v153
	v_add_u32_e32 v151, 0x1000, v151
	v_add_u32_e32 v150, 0x100, v150
	v_add_f32_e32 v153, 1.0, v153
	v_log_f32_e32 v153, v153
	s_nop 0
	v_mul_f32_e32 v155, 0x3f317217, v153
	v_fma_f32 v155, v153, s8, -v155
	v_fmac_f32_e32 v155, 0x3377d1cf, v153
	v_fmac_f32_e32 v155, 0x3f317217, v153
	v_sub_f32_e32 v153, v154, v155
	v_cmp_lt_i32_e32 vcc, 47, v172
	s_or_b64 vcc, s[96:97], vcc
	v_mul_f32_e32 v153, 0x3d800000, v153
	v_cndmask_b32_e32 v153, 0, v153, vcc
	v_add_f32_e32 v170, v152, v153
	v_add_u32_e32 v152, 0x12000, v171
	ds_write_b32 v152, v170
	ds_read_b128 v[152:155], v173 offset:64
	ds_read_b128 v[156:159], v173 offset:80
	ds_read_b128 v[160:163], v173 offset:96
	ds_read_b128 v[164:167], v173 offset:112
	s_waitcnt lgkmcnt(0)
	v_pk_mul_f32 v[218:219], v[202:203], v[152:153]
	v_pk_mul_f32 v[220:221], v[210:211], v[160:161]
	v_pk_fma_f32 v[218:219], v[204:205], v[154:155], v[218:219]
	v_pk_fma_f32 v[220:221], v[212:213], v[162:163], v[220:221]
	v_pk_fma_f32 v[218:219], v[206:207], v[156:157], v[218:219]
	v_pk_fma_f32 v[220:221], v[214:215], v[164:165], v[220:221]
	v_pk_fma_f32 v[218:219], v[208:209], v[158:159], v[218:219]
	v_pk_fma_f32 v[220:221], v[216:217], v[166:167], v[220:221]
	s_nop 0
	v_pk_add_f32 v[218:219], v[218:219], v[220:221]
	s_nop 0
	v_add_f32_e32 v152, v105, v218
	v_add_f32_e32 v152, v152, v219
	v_min_f32_e32 v153, 0, v152
	v_mul_f32_e64 v152, |v152|, s6
	v_exp_f32_e32 v152, v152
	s_nop 0
	v_add_f32_e32 v152, 1.0, v152
	v_log_f32_e32 v152, v152
	s_nop 0
	v_mul_f32_e32 v154, 0x3f317217, v152
	v_fma_f32 v154, v152, s8, -v154
	v_fmac_f32_e32 v154, 0x3377d1cf, v152
	v_fmac_f32_e32 v154, 0x3f317217, v152
	v_sub_f32_e32 v152, v153, v154
	v_cmp_lt_i32_e32 vcc, 46, v172
	s_or_b64 vcc, s[96:97], vcc
	v_mul_f32_e32 v152, 0x3d800000, v152
	v_cndmask_b32_e32 v152, 0, v152, vcc
	v_add_f32_e32 v170, v170, v152
	v_add_u32_e32 v152, 0x12400, v171
	ds_write_b32 v152, v170
	ds_read_b128 v[152:155], v173 offset:128
	ds_read_b128 v[156:159], v173 offset:144
	ds_read_b128 v[160:163], v173 offset:160
	ds_read_b128 v[164:167], v173 offset:176
	v_add_u32_e32 v172, 3, v172
	s_waitcnt lgkmcnt(0)
	v_pk_mul_f32 v[218:219], v[202:203], v[152:153]
	v_pk_mul_f32 v[220:221], v[210:211], v[160:161]
	v_pk_fma_f32 v[218:219], v[204:205], v[154:155], v[218:219]
	v_pk_fma_f32 v[220:221], v[212:213], v[162:163], v[220:221]
	v_pk_fma_f32 v[218:219], v[206:207], v[156:157], v[218:219]
	v_pk_fma_f32 v[220:221], v[214:215], v[164:165], v[220:221]
	v_pk_fma_f32 v[218:219], v[208:209], v[158:159], v[218:219]
	v_pk_fma_f32 v[220:221], v[216:217], v[166:167], v[220:221]
	s_nop 0
	v_pk_add_f32 v[218:219], v[218:219], v[220:221]
	s_nop 0
	v_add_f32_e32 v152, v105, v218
	v_add_f32_e32 v152, v152, v219
	v_min_f32_e32 v153, 0, v152
	v_mul_f32_e64 v152, |v152|, s6
	v_exp_f32_e32 v152, v152
	s_nop 0
	v_add_f32_e32 v152, 1.0, v152
	v_log_f32_e32 v152, v152
	s_nop 0
	v_mul_f32_e32 v154, 0x3f317217, v152
	v_fma_f32 v154, v152, s8, -v154
	v_fmac_f32_e32 v154, 0x3377d1cf, v152
	v_fmac_f32_e32 v154, 0x3f317217, v152
	v_sub_f32_e32 v152, v153, v154
	v_cmp_lt_i32_e32 vcc, 47, v174
	s_or_b64 vcc, s[96:97], vcc
	v_mul_f32_e32 v152, 0x3d800000, v152
	v_cndmask_b32_e32 v152, 0, v152, vcc
	v_add_f32_e32 v170, v170, v152
	v_add_u32_e32 v152, 0x12800, v171
	ds_write_b32 v152, v170
	ds_read_b128 v[152:155], v173 offset:192
	ds_read_b128 v[156:159], v173 offset:208
	ds_read_b128 v[160:163], v173 offset:224
	ds_read_b128 v[164:167], v173 offset:240
	s_waitcnt lgkmcnt(0)
	v_pk_mul_f32 v[218:219], v[202:203], v[152:153]
	v_pk_mul_f32 v[220:221], v[210:211], v[160:161]
	v_pk_fma_f32 v[218:219], v[204:205], v[154:155], v[218:219]
	v_pk_fma_f32 v[220:221], v[212:213], v[162:163], v[220:221]
	v_pk_fma_f32 v[218:219], v[206:207], v[156:157], v[218:219]
	v_pk_fma_f32 v[220:221], v[214:215], v[164:165], v[220:221]
	v_pk_fma_f32 v[218:219], v[208:209], v[158:159], v[218:219]
	v_pk_fma_f32 v[220:221], v[216:217], v[166:167], v[220:221]
	s_nop 0
	v_pk_add_f32 v[218:219], v[218:219], v[220:221]
	s_nop 0
	v_add_f32_e32 v152, v105, v218
	v_add_f32_e32 v152, v152, v219
	v_min_f32_e32 v153, 0, v152
	v_mul_f32_e64 v152, |v152|, s6
	v_exp_f32_e32 v152, v152
	s_nop 0
	v_add_f32_e32 v152, 1.0, v152
	v_log_f32_e32 v152, v152
	s_nop 0
	v_mul_f32_e32 v154, 0x3f317217, v152
	v_fma_f32 v154, v152, s8, -v154
	v_fmac_f32_e32 v154, 0x3377d1cf, v152
	v_fmac_f32_e32 v154, 0x3f317217, v152
	v_sub_f32_e32 v152, v153, v154
	v_cmp_lt_i32_e32 vcc, 47, v172
	s_or_b64 vcc, s[96:97], vcc
	v_mul_f32_e32 v152, 0x3d800000, v152
	v_cndmask_b32_e32 v152, 0, v152, vcc
	v_add_f32_e32 v152, v170, v152
	v_add_u32_e32 v153, 0x12c00, v171
	s_cmp_eq_u32 s0, 32
	ds_write_b32 v153, v152
	s_cbranch_scc0 .LBB0_673
; __device__ __forceinline__ unsigned cvt_pk_bf16(float lo, float hi) { unsigned r; asm volatile("v_cvt_pk_bf16_f32 %0, %1, %2" : "=v"(r) : "v"(lo), "v"(hi)); return r; }
; #define LAS __attribute__((address_space(3)))
; __device__ __forceinline__ void gla_prep_phase(const Ctx& c, int j, LAS unsigned char* lds) {
;     ...
;         TOT[half * 256 + d] = run;
;         __syncthreads();
;         const size_t tile = (size_t)(dir * 16 + bh) * NCH + ch;
;         bf16_t* qdst = QD + tile * (64 * 256);
;         {
;             const int dq = (c.tid & 63) * 4, i0 = (c.tid >> 6) * 8, hf = i0 >> 5;
;             const f32x4 t0 = *(const LAS f32x4*)(TOT + dq), t1 = *(const LAS f32x4*)(TOT + 256 + dq), total = t0 + t1;
;             const f32x4 off0 = hf ? t0 : (f32x4){0.f, 0.f, 0.f, 0.f}, sbase = hf ? t1 : total;
;             f32x4 etot; etot.x = __expf(total.x); etot.y = __expf(total.y); etot.z = __expf(total.z); etot.w = __expf(total.w);
;             f32x4 prev = (i0 & 31) ? *(const LAS f32x4*)(CUM + (i0 - 1) * 256 + dq) : (f32x4){0.f, 0.f, 0.f, 0.f};
;             float kf[4][8];
; #pragma unroll
;             for (int e = 0; e < 8; ++e) { const int i = i0 + e;
;                 const f32x4 incl = *(const LAS f32x4*)(CUM + i * 256 + dq);
;                 const f32x4 cum = (dir == 0) ? (off0 + incl) : (sbase - prev); prev = incl;
;                 const u32x2 qw = *(const LAS u32x2*)(QL + i * 528 + dq * 2), kw = *(const LAS u32x2*)(KL + i * 528 + dq * 2);
;                 const float qv[4] = {__uint_as_float(qw.x << 16), __uint_as_float(qw.x & 0xffff0000u), __uint_as_float(qw.y << 16), __uint_as_float(qw.y & 0xffff0000u)};
;                 const float kv[4] = {__uint_as_float(kw.x << 16), __uint_as_float(kw.x & 0xffff0000u), __uint_as_float(kw.y << 16), __uint_as_float(kw.y & 0xffff0000u)};
;                 float qd[4], ki[4];
; #pragma unroll
;                 for (int jx = 0; jx < 4; ++jx) { const float ec = __expf(cum[jx]), rc = __builtin_amdgcn_rcpf(ec);
;                     qd[jx] = qv[jx] * ec * (1.f / 16.f); ki[jx] = kv[jx] * rc; kf[jx][e] = ki[jx] * etot[jx]; }
;                 *(LAS u32x2*)(QL + i * 528 + dq * 2) = (u32x2){pg8::cvt_pk_bf16(qd[0], qd[1]), pg8::cvt_pk_bf16(qd[2], qd[3])};
;                 *(LAS u32x2*)(KL + i * 528 + dq * 2) = (u32x2){pg8::cvt_pk_bf16(ki[0], ki[1]), pg8::cvt_pk_bf16(ki[2], ki[3])}; }
	ds_write_b32 v91, v152 offset:4096
	s_waitcnt lgkmcnt(0)
	s_barrier
	ds_read_b128 v[0:3], v128 offset:4096
	ds_read_b128 v[8:11], v128 offset:5120
	v_mov_b32_e32 v4, 0
	v_mov_b32_e32 v5, 0
	v_mov_b32_e32 v6, 0
	v_mov_b32_e32 v7, 0
	s_and_saveexec_b64 s[0:1], s[38:39]
	ds_read_b128 v[4:7], v132
	s_or_b64 exec, exec, s[0:1]
	s_waitcnt lgkmcnt(0)
	v_pk_add_f32 v[150:151], v[0:1], v[8:9]
	s_lshl_b32 s0, s94, 4
	v_pk_add_f32 v[154:155], v[2:3], v[10:11]
	v_cndmask_b32_e64 v14, v9, v151, s[36:37]
	v_cndmask_b32_e64 v9, v3, 0, s[36:37]
	v_add_u32_e32 v3, v130, v129
	s_add_i32 s0, s0, s13
	v_cndmask_b32_e64 v12, v11, v155, s[36:37]
	v_cndmask_b32_e64 v13, v10, v154, s[36:37]
	v_cndmask_b32_e64 v15, v8, v150, s[36:37]
	v_cndmask_b32_e64 v11, v1, 0, s[36:37]
	v_cndmask_b32_e64 v10, v0, 0, s[36:37]
	v_mul_f32_e32 v0, 0x3fb8aa3b, v150
	v_mul_f32_e32 v1, 0x3fb8aa3b, v151
	ds_read_b128 v[150:153], v3
	s_mul_hi_i32 s1, s0, 0x41
	s_mulk_i32 s0, 0x41
	s_ashr_i32 s13, s12, 31
	s_add_u32 s94, s0, s12
	s_addc_u32 s95, s1, s13
	s_add_i32 s0, s11, 0x40f
	s_cmpk_lt_u32 s0, 0x81f
	v_cndmask_b32_e64 v8, v2, 0, s[36:37]
	v_mul_f32_e32 v2, 0x3fb8aa3b, v154
	v_mul_f32_e32 v3, 0x3fb8aa3b, v155
	s_waitcnt lgkmcnt(0)
	v_pk_add_f32 v[154:155], v[10:11], v[150:151]
	v_sub_f32_e32 v159, v15, v4
	v_sub_f32_e32 v160, v14, v5
	s_cselect_b64 s[54:55], -1, 0
	v_sub_f32_e32 v105, v13, v6
	v_sub_f32_e32 v158, v12, v7
	ds_read2st64_b64 v[4:7], v138 offset0:12 offset1:78
	v_cndmask_b32_e64 v155, v160, v155, s[54:55]
	v_cndmask_b32_e64 v154, v159, v154, s[54:55]
	v_mul_f32_e32 v154, 0x3fb8aa3b, v154
	v_mul_f32_e32 v155, 0x3fb8aa3b, v155
	v_exp_f32_e32 v154, v154
	v_exp_f32_e32 v155, v155
	v_pk_add_f32 v[156:157], v[8:9], v[152:153]
	s_waitcnt lgkmcnt(0)
	v_lshlrev_b32_e32 v159, 16, v6
	v_cndmask_b32_e64 v157, v158, v157, s[54:55]
	v_cndmask_b32_e64 v105, v105, v156, s[54:55]
	v_lshlrev_b32_e32 v156, 16, v4
	v_and_b32_e32 v4, 0xffff0000, v4
	v_rcp_f32_e32 v161, v154
	v_mul_f32_e32 v154, v154, v156
	v_rcp_f32_e32 v156, v155
	v_mul_f32_e32 v4, v155, v4
	v_mul_f32_e32 v105, 0x3fb8aa3b, v105
	v_mul_f32_e32 v155, 0x3fb8aa3b, v157
	v_exp_f32_e32 v105, v105
	v_exp_f32_e32 v155, v155
	v_and_b32_e32 v6, 0xffff0000, v6
	v_lshlrev_b32_e32 v158, 16, v5
	v_and_b32_e32 v5, 0xffff0000, v5
	v_mul_f32_e32 v6, v156, v6
	v_rcp_f32_e32 v156, v105
	v_rcp_f32_e32 v157, v155
	v_mul_f32_e32 v5, v155, v5
	v_mul_f32_e32 v4, 0x3d800000, v4
	v_mul_f32_e32 v105, v105, v158
	v_mul_f32_e32 v5, 0x3d800000, v5
	v_lshlrev_b32_e32 v160, 16, v7
	v_and_b32_e32 v7, 0xffff0000, v7
	v_mul_f32_e32 v154, 0x3d800000, v154
	v_mul_f32_e32 v105, 0x3d800000, v105
	v_cvt_pk_bf16_f32 v4, v154, v4
	v_cvt_pk_bf16_f32 v5, v105, v5
	v_mul_f32_e32 v159, v161, v159
	v_mul_f32_e32 v158, v156, v160
	v_mul_f32_e32 v160, v157, v7
	ds_write_b64 v138, v[4:5] offset:6144
	v_cvt_pk_bf16_f32 v4, v159, v6
	v_cvt_pk_bf16_f32 v5, v158, v160
	ds_write_b64 v138, v[4:5] offset:39936
	ds_read_b128 v[154:157], v139
	v_exp_f32_e32 v0, v0
	v_exp_f32_e32 v2, v2
	v_sub_f32_e32 v105, v15, v150
	v_sub_f32_e32 v162, v14, v151
	v_mul_f32_e32 v7, v0, v159
	v_mul_f32_e32 v5, v2, v158
	s_waitcnt lgkmcnt(0)
	v_pk_add_f32 v[158:159], v[10:11], v[154:155]
	v_add_u32_e32 v150, 16, v138
	v_cndmask_b32_e64 v105, v105, v158, s[54:55]
	v_mul_f32_e32 v105, 0x3fb8aa3b, v105
	v_exp_f32_e32 v105, v105
	v_exp_f32_e32 v3, v3
	v_sub_f32_e32 v163, v13, v152
	v_sub_f32_e32 v164, v12, v153
	ds_read2st64_b64 v[150:153], v150 offset0:13 offset1:79
	v_cndmask_b32_e64 v159, v162, v159, s[54:55]
	v_mul_f32_e32 v159, 0x3fb8aa3b, v159
	v_rcp_f32_e32 v165, v105
	v_exp_f32_e32 v159, v159
	v_mul_f32_e32 v4, v3, v160
	v_pk_add_f32 v[160:161], v[8:9], v[156:157]
	s_waitcnt lgkmcnt(0)
	v_lshlrev_b32_e32 v158, 16, v150
	v_cndmask_b32_e64 v160, v163, v160, s[54:55]
	v_lshlrev_b32_e32 v163, 16, v152
	v_mul_f32_e32 v105, v105, v158
	v_mul_f32_e32 v158, v165, v163
	v_rcp_f32_e32 v163, v159
	v_cndmask_b32_e64 v161, v164, v161, s[54:55]
	v_and_b32_e32 v150, 0xffff0000, v150
	v_and_b32_e32 v152, 0xffff0000, v152
	v_mul_f32_e32 v150, v159, v150
	v_mul_f32_e32 v159, 0x3fb8aa3b, v160
	v_mul_f32_e32 v160, v163, v152
	v_mul_f32_e32 v152, 0x3fb8aa3b, v161
	v_exp_f32_e32 v159, v159
	v_exp_f32_e32 v152, v152
	v_lshlrev_b32_e32 v162, 16, v151
	v_and_b32_e32 v151, 0xffff0000, v151
	v_rcp_f32_e32 v161, v159
	v_mul_f32_e32 v159, v159, v162
	v_rcp_f32_e32 v162, v152
	v_mul_f32_e32 v151, v152, v151
	v_mul_f32_e32 v150, 0x3d800000, v150
	v_mul_f32_e32 v151, 0x3d800000, v151
	v_lshlrev_b32_e32 v164, 16, v153
	v_and_b32_e32 v153, 0xffff0000, v153
	v_mul_f32_e32 v105, 0x3d800000, v105
	v_mul_f32_e32 v159, 0x3d800000, v159
	v_cvt_pk_bf16_f32 v150, v105, v150
	v_cvt_pk_bf16_f32 v151, v159, v151
	v_mul_f32_e32 v161, v161, v164
	v_mul_f32_e32 v162, v162, v153
	ds_write_b64 v138, v[150:151] offset:6672
	v_cvt_pk_bf16_f32 v150, v158, v160
	v_cvt_pk_bf16_f32 v151, v161, v162
	ds_write_b64 v138, v[150:151] offset:40464
	ds_read_b128 v[150:153], v140
	v_mul_f32_e32 v163, v0, v158
	v_mul_f32_e32 v105, v3, v162
	v_sub_f32_e32 v162, v15, v154
	v_sub_f32_e32 v166, v14, v155
	s_waitcnt lgkmcnt(0)
	v_pk_add_f32 v[158:159], v[10:11], v[150:151]
	v_add_u32_e32 v154, 32, v138
	v_cndmask_b32_e64 v158, v162, v158, s[54:55]
	v_mul_f32_e32 v158, 0x3fb8aa3b, v158
	v_exp_f32_e32 v158, v158
	v_exp_f32_e32 v1, v1
	v_sub_f32_e32 v167, v13, v156
	v_sub_f32_e32 v168, v12, v157
	ds_read2st64_b64 v[154:157], v154 offset0:14 offset1:80
	v_cndmask_b32_e64 v159, v166, v159, s[54:55]
	v_mul_f32_e32 v159, 0x3fb8aa3b, v159
	v_rcp_f32_e32 v169, v158
	v_exp_f32_e32 v159, v159
	v_mul_f32_e32 v164, v1, v160
	v_mul_f32_e32 v165, v2, v161
	v_pk_add_f32 v[160:161], v[8:9], v[152:153]
	s_waitcnt lgkmcnt(0)
; __device__ __forceinline__ unsigned cvt_pk_bf16(float lo, float hi) { unsigned r; asm volatile("v_cvt_pk_bf16_f32 %0, %1, %2" : "=v"(r) : "v"(lo), "v"(hi)); return r; }
; #define LAS __attribute__((address_space(3)))
; __device__ __forceinline__ void gla_prep_phase(const Ctx& c, int j, LAS unsigned char* lds) {
;     ...
;             for (int e = 0; e < 8; ++e) { const int i = i0 + e;
;                 const f32x4 incl = *(const LAS f32x4*)(CUM + i * 256 + dq);
;                 const f32x4 cum = (dir == 0) ? (off0 + incl) : (sbase - prev); prev = incl;
;                 const u32x2 qw = *(const LAS u32x2*)(QL + i * 528 + dq * 2), kw = *(const LAS u32x2*)(KL + i * 528 + dq * 2);
;                 const float qv[4] = {__uint_as_float(qw.x << 16), __uint_as_float(qw.x & 0xffff0000u), __uint_as_float(qw.y << 16), __uint_as_float(qw.y & 0xffff0000u)};
;                 const float kv[4] = {__uint_as_float(kw.x << 16), __uint_as_float(kw.x & 0xffff0000u), __uint_as_float(kw.y << 16), __uint_as_float(kw.y & 0xffff0000u)};
;                 float qd[4], ki[4];
; #pragma unroll
;                 for (int jx = 0; jx < 4; ++jx) { const float ec = __expf(cum[jx]), rc = __builtin_amdgcn_rcpf(ec);
;                     qd[jx] = qv[jx] * ec * (1.f / 16.f); ki[jx] = kv[jx] * rc; kf[jx][e] = ki[jx] * etot[jx]; }
;                 *(LAS u32x2*)(QL + i * 528 + dq * 2) = (u32x2){pg8::cvt_pk_bf16(qd[0], qd[1]), pg8::cvt_pk_bf16(qd[2], qd[3])};
;                 *(LAS u32x2*)(KL + i * 528 + dq * 2) = (u32x2){pg8::cvt_pk_bf16(ki[0], ki[1]), pg8::cvt_pk_bf16(ki[2], ki[3])}; }
	v_lshlrev_b32_e32 v162, 16, v154
	v_cndmask_b32_e64 v160, v167, v160, s[54:55]
	v_lshlrev_b32_e32 v167, 16, v156
	v_mul_f32_e32 v158, v158, v162
	v_mul_f32_e32 v162, v169, v167
	v_rcp_f32_e32 v167, v159
	v_cndmask_b32_e64 v161, v168, v161, s[54:55]
	v_and_b32_e32 v154, 0xffff0000, v154
	v_and_b32_e32 v156, 0xffff0000, v156
	v_mul_f32_e32 v154, v159, v154
	v_mul_f32_e32 v159, 0x3fb8aa3b, v160
	v_mul_f32_e32 v160, v167, v156
	v_mul_f32_e32 v156, 0x3fb8aa3b, v161
	v_exp_f32_e32 v159, v159
	v_exp_f32_e32 v156, v156
	v_lshlrev_b32_e32 v166, 16, v155
	v_and_b32_e32 v155, 0xffff0000, v155
	v_rcp_f32_e32 v161, v159
	v_mul_f32_e32 v159, v159, v166
	v_rcp_f32_e32 v166, v156
	v_mul_f32_e32 v155, v156, v155
	v_mul_f32_e32 v154, 0x3d800000, v154
	v_mul_f32_e32 v155, 0x3d800000, v155
	v_lshlrev_b32_e32 v168, 16, v157
	v_and_b32_e32 v157, 0xffff0000, v157
	v_mul_f32_e32 v158, 0x3d800000, v158
	v_mul_f32_e32 v159, 0x3d800000, v159
	v_cvt_pk_bf16_f32 v154, v158, v154
	v_cvt_pk_bf16_f32 v155, v159, v155
	v_mul_f32_e32 v161, v161, v168
	v_mul_f32_e32 v166, v166, v157
	ds_write_b64 v138, v[154:155] offset:7200
	v_cvt_pk_bf16_f32 v154, v162, v160
	v_cvt_pk_bf16_f32 v155, v161, v166
	ds_write_b64 v138, v[154:155] offset:40992
	ds_read_b128 v[154:157], v141
	v_sub_f32_e32 v169, v15, v150
	v_sub_f32_e32 v170, v14, v151
	v_add_u32_e32 v150, 48, v138
	v_sub_f32_e32 v171, v13, v152
	s_waitcnt lgkmcnt(0)
	v_pk_add_f32 v[158:159], v[10:11], v[154:155]
	v_sub_f32_e32 v172, v12, v153
	v_cndmask_b32_e64 v158, v169, v158, s[54:55]
	v_mul_f32_e32 v158, 0x3fb8aa3b, v158
	v_exp_f32_e32 v158, v158
	ds_read2st64_b64 v[150:153], v150 offset0:15 offset1:81
	v_cndmask_b32_e64 v159, v170, v159, s[54:55]
	v_mul_f32_e32 v159, 0x3fb8aa3b, v159
	v_rcp_f32_e32 v173, v158
	v_exp_f32_e32 v159, v159
	v_mul_f32_e32 v167, v1, v160
	v_mul_f32_e32 v168, v2, v161
	v_pk_add_f32 v[160:161], v[8:9], v[156:157]
	s_waitcnt lgkmcnt(0)
	v_lshlrev_b32_e32 v169, 16, v150
	v_cndmask_b32_e64 v160, v171, v160, s[54:55]
	v_lshlrev_b32_e32 v171, 16, v152
	v_mul_f32_e32 v158, v158, v169
	v_mul_f32_e32 v169, v173, v171
	v_rcp_f32_e32 v171, v159
	v_cndmask_b32_e64 v161, v172, v161, s[54:55]
	v_and_b32_e32 v150, 0xffff0000, v150
	v_and_b32_e32 v152, 0xffff0000, v152
	v_mul_f32_e32 v150, v159, v150
	v_mul_f32_e32 v159, 0x3fb8aa3b, v160
	v_mul_f32_e32 v160, v171, v152
	v_mul_f32_e32 v152, 0x3fb8aa3b, v161
	v_exp_f32_e32 v159, v159
	v_exp_f32_e32 v152, v152
	v_lshlrev_b32_e32 v170, 16, v151
	v_and_b32_e32 v151, 0xffff0000, v151
	v_rcp_f32_e32 v161, v159
	v_mul_f32_e32 v159, v159, v170
	v_rcp_f32_e32 v170, v152
	v_mul_f32_e32 v151, v152, v151
	v_mul_f32_e32 v150, 0x3d800000, v150
	v_mul_f32_e32 v151, 0x3d800000, v151
	v_lshlrev_b32_e32 v172, 16, v153
	v_and_b32_e32 v153, 0xffff0000, v153
	v_mul_f32_e32 v158, 0x3d800000, v158
	v_mul_f32_e32 v159, 0x3d800000, v159
	v_cvt_pk_bf16_f32 v150, v158, v150
	v_cvt_pk_bf16_f32 v151, v159, v151
	v_mul_f32_e32 v161, v161, v172
	v_mul_f32_e32 v170, v170, v153
	ds_write_b64 v138, v[150:151] offset:7728
	v_cvt_pk_bf16_f32 v150, v169, v160
	v_cvt_pk_bf16_f32 v151, v161, v170
	ds_write_b64 v138, v[150:151] offset:41520
	ds_read_b128 v[150:153], v142
	v_sub_f32_e32 v173, v15, v154
	v_sub_f32_e32 v174, v14, v155
	v_add_u32_e32 v154, 64, v138
	v_sub_f32_e32 v175, v13, v156
	s_waitcnt lgkmcnt(0)
	v_pk_add_f32 v[158:159], v[10:11], v[150:151]
	v_sub_f32_e32 v176, v12, v157
	v_cndmask_b32_e64 v158, v173, v158, s[54:55]
	v_mul_f32_e32 v158, 0x3fb8aa3b, v158
	v_exp_f32_e32 v158, v158
	ds_read2st64_b64 v[154:157], v154 offset0:16 offset1:82
	v_cndmask_b32_e64 v159, v174, v159, s[54:55]
	v_mul_f32_e32 v159, 0x3fb8aa3b, v159
	v_rcp_f32_e32 v177, v158
	v_exp_f32_e32 v159, v159
	v_mul_f32_e32 v171, v1, v160
	v_mul_f32_e32 v172, v2, v161
	v_pk_add_f32 v[160:161], v[8:9], v[152:153]
	s_waitcnt lgkmcnt(0)
	v_lshlrev_b32_e32 v173, 16, v154
	v_cndmask_b32_e64 v160, v175, v160, s[54:55]
	v_lshlrev_b32_e32 v175, 16, v156
	v_mul_f32_e32 v158, v158, v173
	v_mul_f32_e32 v173, v177, v175
	v_rcp_f32_e32 v175, v159
	v_cndmask_b32_e64 v161, v176, v161, s[54:55]
	v_and_b32_e32 v154, 0xffff0000, v154
	v_and_b32_e32 v156, 0xffff0000, v156
	v_mul_f32_e32 v154, v159, v154
	v_mul_f32_e32 v159, 0x3fb8aa3b, v160
	v_mul_f32_e32 v160, v175, v156
	v_mul_f32_e32 v156, 0x3fb8aa3b, v161
	v_exp_f32_e32 v159, v159
	v_exp_f32_e32 v156, v156
	v_lshlrev_b32_e32 v174, 16, v155
	v_and_b32_e32 v155, 0xffff0000, v155
	v_rcp_f32_e32 v161, v159
	v_mul_f32_e32 v159, v159, v174
	v_rcp_f32_e32 v174, v156
	v_mul_f32_e32 v155, v156, v155
	v_mul_f32_e32 v154, 0x3d800000, v154
	v_mul_f32_e32 v155, 0x3d800000, v155
	v_lshlrev_b32_e32 v176, 16, v157
	v_and_b32_e32 v157, 0xffff0000, v157
	v_mul_f32_e32 v158, 0x3d800000, v158
	v_mul_f32_e32 v159, 0x3d800000, v159
	v_cvt_pk_bf16_f32 v154, v158, v154
	v_cvt_pk_bf16_f32 v155, v159, v155
	v_mul_f32_e32 v161, v161, v176
	v_mul_f32_e32 v174, v174, v157
	ds_write_b64 v138, v[154:155] offset:8256
	v_cvt_pk_bf16_f32 v154, v173, v160
	v_cvt_pk_bf16_f32 v155, v161, v174
	ds_write_b64 v138, v[154:155] offset:42048
	ds_read_b128 v[154:157], v143
	v_sub_f32_e32 v177, v15, v150
	v_sub_f32_e32 v178, v14, v151
	v_add_u32_e32 v150, 0x50, v138
	v_sub_f32_e32 v179, v13, v152
	s_waitcnt lgkmcnt(0)
	v_pk_add_f32 v[158:159], v[10:11], v[154:155]
	v_sub_f32_e32 v180, v12, v153
	v_cndmask_b32_e64 v158, v177, v158, s[54:55]
	v_mul_f32_e32 v158, 0x3fb8aa3b, v158
	v_exp_f32_e32 v158, v158
	ds_read2st64_b64 v[150:153], v150 offset0:17 offset1:83
	v_cndmask_b32_e64 v159, v178, v159, s[54:55]
	v_mul_f32_e32 v159, 0x3fb8aa3b, v159
	v_rcp_f32_e32 v181, v158
	v_exp_f32_e32 v159, v159
	v_mul_f32_e32 v175, v1, v160
	v_mul_f32_e32 v176, v2, v161
	v_pk_add_f32 v[160:161], v[8:9], v[156:157]
	s_waitcnt lgkmcnt(0)
; __device__ __forceinline__ unsigned cvt_pk_bf16(float lo, float hi) { unsigned r; asm volatile("v_cvt_pk_bf16_f32 %0, %1, %2" : "=v"(r) : "v"(lo), "v"(hi)); return r; }
; #define LAS __attribute__((address_space(3)))
; __device__ __forceinline__ void gla_prep_phase(const Ctx& c, int j, LAS unsigned char* lds) {
;     ...
;             for (int e = 0; e < 8; ++e) { const int i = i0 + e;
;                 const f32x4 incl = *(const LAS f32x4*)(CUM + i * 256 + dq);
;                 const f32x4 cum = (dir == 0) ? (off0 + incl) : (sbase - prev); prev = incl;
;                 const u32x2 qw = *(const LAS u32x2*)(QL + i * 528 + dq * 2), kw = *(const LAS u32x2*)(KL + i * 528 + dq * 2);
;                 const float qv[4] = {__uint_as_float(qw.x << 16), __uint_as_float(qw.x & 0xffff0000u), __uint_as_float(qw.y << 16), __uint_as_float(qw.y & 0xffff0000u)};
;                 const float kv[4] = {__uint_as_float(kw.x << 16), __uint_as_float(kw.x & 0xffff0000u), __uint_as_float(kw.y << 16), __uint_as_float(kw.y & 0xffff0000u)};
;                 float qd[4], ki[4];
; #pragma unroll
;                 for (int jx = 0; jx < 4; ++jx) { const float ec = __expf(cum[jx]), rc = __builtin_amdgcn_rcpf(ec);
;                     qd[jx] = qv[jx] * ec * (1.f / 16.f); ki[jx] = kv[jx] * rc; kf[jx][e] = ki[jx] * etot[jx]; }
;                 *(LAS u32x2*)(QL + i * 528 + dq * 2) = (u32x2){pg8::cvt_pk_bf16(qd[0], qd[1]), pg8::cvt_pk_bf16(qd[2], qd[3])};
;                 *(LAS u32x2*)(KL + i * 528 + dq * 2) = (u32x2){pg8::cvt_pk_bf16(ki[0], ki[1]), pg8::cvt_pk_bf16(ki[2], ki[3])}; }
;             bf16_t* kdst = KET + tile * (256 * 64) + (size_t)dq * 64 + i0;
; #pragma unroll
;             for (int jx = 0; jx < 4; ++jx)
;                 *(u32x4*)(kdst + jx * 64) = (u32x4){pg8::cvt_pk_bf16(kf[jx][0], kf[jx][1]), pg8::cvt_pk_bf16(kf[jx][2], kf[jx][3]), pg8::cvt_pk_bf16(kf[jx][4], kf[jx][5]), pg8::cvt_pk_bf16(kf[jx][6], kf[jx][7])};
;             if (i0 == 0) *(f32x4*)(DEC + tile * 256 + dq) = etot;
	v_lshlrev_b32_e32 v177, 16, v150
	v_cndmask_b32_e64 v160, v179, v160, s[54:55]
	v_lshlrev_b32_e32 v179, 16, v152
	v_mul_f32_e32 v158, v158, v177
	v_mul_f32_e32 v177, v181, v179
	v_rcp_f32_e32 v179, v159
	v_cndmask_b32_e64 v161, v180, v161, s[54:55]
	v_and_b32_e32 v150, 0xffff0000, v150
	v_and_b32_e32 v152, 0xffff0000, v152
	v_mul_f32_e32 v150, v159, v150
	v_mul_f32_e32 v159, 0x3fb8aa3b, v160
	v_mul_f32_e32 v160, v179, v152
	v_mul_f32_e32 v152, 0x3fb8aa3b, v161
	v_exp_f32_e32 v159, v159
	v_exp_f32_e32 v152, v152
	v_lshlrev_b32_e32 v178, 16, v151
	v_and_b32_e32 v151, 0xffff0000, v151
	v_rcp_f32_e32 v161, v159
	v_mul_f32_e32 v159, v159, v178
	v_rcp_f32_e32 v178, v152
	v_mul_f32_e32 v151, v152, v151
	v_mul_f32_e32 v150, 0x3d800000, v150
	v_mul_f32_e32 v151, 0x3d800000, v151
	v_lshlrev_b32_e32 v180, 16, v153
	v_and_b32_e32 v153, 0xffff0000, v153
	v_mul_f32_e32 v158, 0x3d800000, v158
	v_mul_f32_e32 v159, 0x3d800000, v159
	v_cvt_pk_bf16_f32 v150, v158, v150
	v_cvt_pk_bf16_f32 v151, v159, v151
	v_mul_f32_e32 v161, v161, v180
	v_mul_f32_e32 v178, v178, v153
	ds_write_b64 v138, v[150:151] offset:8784
	v_cvt_pk_bf16_f32 v150, v177, v160
	v_cvt_pk_bf16_f32 v151, v161, v178
	ds_write_b64 v138, v[150:151] offset:42576
	ds_read_b128 v[150:153], v144
	v_sub_f32_e32 v181, v15, v154
	v_sub_f32_e32 v182, v14, v155
	v_add_u32_e32 v154, 0x60, v138
	v_sub_f32_e32 v183, v13, v156
	s_waitcnt lgkmcnt(0)
	v_pk_add_f32 v[158:159], v[10:11], v[150:151]
	v_sub_f32_e32 v184, v12, v157
	v_cndmask_b32_e64 v158, v181, v158, s[54:55]
	v_mul_f32_e32 v158, 0x3fb8aa3b, v158
	v_exp_f32_e32 v158, v158
	ds_read2st64_b64 v[154:157], v154 offset0:18 offset1:84
	v_cndmask_b32_e64 v159, v182, v159, s[54:55]
	v_mul_f32_e32 v159, 0x3fb8aa3b, v159
	v_rcp_f32_e32 v185, v158
	v_exp_f32_e32 v159, v159
	v_mul_f32_e32 v179, v1, v160
	v_mul_f32_e32 v180, v2, v161
	v_pk_add_f32 v[160:161], v[8:9], v[152:153]
	s_waitcnt lgkmcnt(0)
	v_lshlrev_b32_e32 v181, 16, v154
	v_cndmask_b32_e64 v160, v183, v160, s[54:55]
	v_lshlrev_b32_e32 v183, 16, v156
	v_mul_f32_e32 v158, v158, v181
	v_mul_f32_e32 v181, v185, v183
	v_rcp_f32_e32 v183, v159
	v_cndmask_b32_e64 v161, v184, v161, s[54:55]
	v_and_b32_e32 v154, 0xffff0000, v154
	v_and_b32_e32 v156, 0xffff0000, v156
	v_mul_f32_e32 v154, v159, v154
	v_mul_f32_e32 v159, 0x3fb8aa3b, v160
	v_mul_f32_e32 v160, v183, v156
	v_mul_f32_e32 v156, 0x3fb8aa3b, v161
	v_exp_f32_e32 v159, v159
	v_exp_f32_e32 v156, v156
	v_lshlrev_b32_e32 v182, 16, v155
	v_and_b32_e32 v155, 0xffff0000, v155
	v_rcp_f32_e32 v161, v159
	v_mul_f32_e32 v159, v159, v182
	v_rcp_f32_e32 v182, v156
	v_mul_f32_e32 v155, v156, v155
	v_mul_f32_e32 v154, 0x3d800000, v154
	v_mul_f32_e32 v155, 0x3d800000, v155
	v_lshlrev_b32_e32 v184, 16, v157
	v_and_b32_e32 v157, 0xffff0000, v157
	v_mul_f32_e32 v158, 0x3d800000, v158
	v_mul_f32_e32 v159, 0x3d800000, v159
	v_cvt_pk_bf16_f32 v154, v158, v154
	v_cvt_pk_bf16_f32 v155, v159, v155
	v_mul_f32_e32 v161, v161, v184
	v_mul_f32_e32 v182, v182, v157
	ds_write_b64 v138, v[154:155] offset:9312
	v_cvt_pk_bf16_f32 v154, v181, v160
	v_cvt_pk_bf16_f32 v155, v161, v182
	ds_write_b64 v138, v[154:155] offset:43104
	ds_read_b128 v[154:157], v145
	v_sub_f32_e32 v15, v15, v150
	v_sub_f32_e32 v14, v14, v151
	v_sub_f32_e32 v13, v13, v152
	v_sub_f32_e32 v12, v12, v153
	s_waitcnt lgkmcnt(0)
	v_pk_add_f32 v[154:155], v[10:11], v[154:155]
	v_pk_add_f32 v[156:157], v[8:9], v[156:157]
	v_cndmask_b32_e64 v15, v15, v154, s[54:55]
	v_mul_f32_e32 v15, 0x3fb8aa3b, v15
	v_exp_f32_e32 v15, v15
	ds_read2st64_b64 v[8:11], v146 offset0:12 offset1:78
	v_cndmask_b32_e64 v14, v14, v155, s[54:55]
	v_mul_f32_e32 v14, 0x3fb8aa3b, v14
	v_rcp_f32_e32 v154, v15
	v_exp_f32_e32 v14, v14
	v_cndmask_b32_e64 v13, v13, v156, s[54:55]
	s_waitcnt lgkmcnt(0)
	v_lshlrev_b32_e32 v150, 16, v8
	v_lshlrev_b32_e32 v152, 16, v10
	v_mul_f32_e32 v13, 0x3fb8aa3b, v13
	v_mul_f32_e32 v15, v15, v150
	v_mul_f32_e32 v150, v154, v152
	v_rcp_f32_e32 v154, v14
	v_exp_f32_e32 v13, v13
	v_cndmask_b32_e64 v12, v12, v157, s[54:55]
	v_and_b32_e32 v10, 0xffff0000, v10
	v_mul_f32_e32 v12, 0x3fb8aa3b, v12
	v_mul_f32_e32 v10, v154, v10
	v_rcp_f32_e32 v154, v13
	v_exp_f32_e32 v12, v12
	v_lshlrev_b32_e32 v151, 16, v9
	v_lshlrev_b32_e32 v153, 16, v11
	v_and_b32_e32 v8, 0xffff0000, v8
	v_and_b32_e32 v9, 0xffff0000, v9
	v_mul_f32_e32 v13, v13, v151
	v_mul_f32_e32 v151, v154, v153
	v_rcp_f32_e32 v153, v12
	v_mul_f32_e32 v8, v14, v8
	v_mul_f32_e32 v9, v12, v9
	v_mul_f32_e32 v8, 0x3d800000, v8
	v_mul_f32_e32 v9, 0x3d800000, v9
	v_and_b32_e32 v11, 0xffff0000, v11
	v_mul_f32_e32 v15, 0x3d800000, v15
	v_mul_f32_e32 v13, 0x3d800000, v13
	v_cvt_pk_bf16_f32 v8, v15, v8
	v_cvt_pk_bf16_f32 v9, v13, v9
	s_lshl_b64 s[0:1], s[94:95], 15
	v_mul_f32_e32 v6, v1, v6
	v_mul_f32_e32 v11, v153, v11
	ds_write_b64 v146, v[8:9] offset:6144
	v_cvt_pk_bf16_f32 v8, v150, v10
	v_cvt_pk_bf16_f32 v9, v151, v11
	v_lshl_add_u64 v[12:13], v[92:93], 0, s[0:1]
	v_mul_f32_e32 v162, v0, v162
	v_mul_f32_e32 v169, v0, v169
	v_mul_f32_e32 v173, v0, v173
	v_mul_f32_e32 v177, v0, v177
	v_mul_f32_e32 v158, v0, v181
	v_mul_f32_e32 v152, v0, v150
	v_mul_f32_e32 v14, v1, v10
	v_mul_f32_e32 v153, v3, v11
	ds_write_b64 v146, v[8:9] offset:39936
	v_cvt_pk_bf16_f32 v8, v7, v163
	v_cvt_pk_bf16_f32 v9, v162, v169
	v_cvt_pk_bf16_f32 v10, v173, v177
	v_cvt_pk_bf16_f32 v11, v158, v152
	global_store_dwordx4 v[12:13], v[8:11], off
	v_cvt_pk_bf16_f32 v6, v6, v164
	v_cvt_pk_bf16_f32 v7, v167, v171
	v_mul_f32_e32 v159, v1, v160
	v_mul_f32_e32 v166, v3, v166
	v_cvt_pk_bf16_f32 v8, v175, v179
	v_cvt_pk_bf16_f32 v9, v159, v14
	global_store_dwordx4 v[12:13], v[6:9], off offset:128
	v_mul_f32_e32 v170, v3, v170
	v_mul_f32_e32 v174, v3, v174
	v_cvt_pk_bf16_f32 v6, v5, v165
	v_cvt_pk_bf16_f32 v7, v168, v172
	v_mul_f32_e32 v178, v3, v178
	v_mul_f32_e32 v160, v2, v161
	v_mul_f32_e32 v161, v3, v182
	v_mul_f32_e32 v154, v2, v151
	v_cvt_pk_bf16_f32 v8, v176, v180
	v_cvt_pk_bf16_f32 v9, v160, v154
	global_store_dwordx4 v[12:13], v[6:9], off offset:256
	v_cvt_pk_bf16_f32 v4, v4, v105
	v_cvt_pk_bf16_f32 v5, v166, v170
	s_nop 1
	v_cvt_pk_bf16_f32 v6, v174, v178
	v_cvt_pk_bf16_f32 v7, v161, v153
	global_store_dwordx4 v[12:13], v[4:7], off offset:384
	s_and_saveexec_b64 s[0:1], s[52:53]
	s_cbranch_execz .LBB0_678
	s_lshl_b64 s[12:13], s[94:95], 10
	v_lshl_add_u64 v[4:5], v[94:95], 0, s[12:13]
	global_store_dwordx4 v[4:5], v[0:3], off

; __device__ __forceinline__ unsigned cvt_pk_bf16(float lo, float hi) { unsigned r; asm volatile("v_cvt_pk_bf16_f32 %0, %1, %2" : "=v"(r) : "v"(lo), "v"(hi)); return r; }
; #define LAS __attribute__((address_space(3)))
; __device__ __forceinline__ int crow16(int r, int hi) { return (r & 3) + 8 * (r >> 2) + 4 * hi; }
; __device__ __forceinline__ void gla_prep_phase(const Ctx& c, int j, LAS unsigned char* lds) {
;     ...
;         if (wid < 4) {
;             const int ib = wid & 1, sb = wid >> 1; f32x16 acc = {};
; #pragma unroll 4
;             for (int ks = 0; ks < 16; ++ks) {
;                 const bf16x8 a = *(const LAS bf16x8*)(QL + (32 * ib + r32) * 528 + (ks * 16 + hi * 8) * 2);
;                 const bf16x8 bb = *(const LAS bf16x8*)(KL + (32 * sb + r32) * 528 + (ks * 16 + hi * 8) * 2);
;                 acc = __builtin_amdgcn_mfma_f32_32x32x16_bf16(a, bb, acc, 0, 0, 0); }
;             bf16_t* pdst = PM + tile * (64 * 64);
; #pragma unroll
;             for (int r = 0; r < 16; ++r) { const int i = 32 * ib + crow16(r, hi), s = 32 * sb + r32;
;                 const bool keep = (dir == 0) ? (s <= i) : (s > i);
;                 pdst[i * 64 + s] = (bf16_t)(pg8::cvt_pk_bf16(keep ? acc[r] : 0.f, 0.f) & 0xffffu); }
;         }
;     }
.LBB0_737:
	s_or_b64 exec, exec, s[2:3]
	s_waitcnt lgkmcnt(0)
	s_barrier
	s_nop 0
	s_nop 0
	s_nop 0
	s_nop 0
	s_nop 0
	s_nop 0
	s_nop 0
	s_nop 0
	s_nop 0
	s_nop 0
	s_nop 0
	s_nop 0
	s_nop 0
	s_nop 0
	s_nop 0
	s_nop 0
	s_nop 0
	s_nop 0
	s_nop 0
	s_nop 0
	s_nop 0
	s_nop 0
	s_nop 0
	s_nop 0
	s_nop 0
	s_nop 0
	s_nop 0
	s_nop 0
	s_nop 0
	s_nop 0
	s_nop 0
	s_nop 0
	s_nop 0
	s_nop 0
	s_nop 0
	s_nop 0
	s_nop 0
	s_nop 0
	s_nop 0
	s_nop 0
	s_nop 0
	s_nop 0
	s_nop 0
	s_nop 0
	s_nop 0
	s_nop 0
	s_nop 0
	s_nop 0
	s_nop 0
	s_nop 0
	s_nop 0
	s_nop 0
	s_nop 0
	s_nop 0
	s_nop 0
	s_nop 0
	s_nop 0
	s_nop 0
	s_nop 0
	s_nop 0
	s_nop 0
	s_nop 0
	s_nop 0
	s_nop 0
	s_nop 0
	s_nop 0
	s_nop 0
	s_nop 0
	s_nop 0
	s_nop 0
	s_nop 0
	s_nop 0
	s_nop 0
	s_nop 0
	s_nop 0
	s_nop 0
	s_nop 0
	s_nop 0
	s_nop 0
	s_nop 0
	s_nop 0
	s_nop 0
	s_nop 0
	s_nop 0
	s_nop 0
	s_nop 0
	s_nop 0
	s_nop 0
	s_nop 0
	s_nop 0
	s_nop 0
	s_nop 0
	s_nop 0
	s_nop 0
	s_nop 0

; __device__ __forceinline__ unsigned short f2bf(float f) { unsigned u = __float_as_uint(f); return (unsigned short)((u + 0x7fffu + ((u >> 16) & 1u)) >> 16); }
; __device__ __forceinline__ unsigned f2bf(float f) { return pk2(f, 0.f) & 0xffffu; }
; __device__ __forceinline__ void gla_scan_phase(const Ctx& c, LAS unsigned char* lds) {
;     ...
;             if (wid < 4) {
;                 const int ib = wid & 1, eb = wid >> 1;
;                 const int col = h * 512 + es * 64 + 32 * eb + r32;
;                 const int rbase = (ch == 0 ? NREAL + b * NMETA - 48 : b * SEQ + (ch - 1) * 64) + 32 * ib + 4 * hi;
;                 bf16_t* obase = dir == 0 ? Pw : A; const int ostride = dir == 0 ? GLA_NP : DM;
;                 bf16_t* dst0 = obase + (size_t)rbase * ostride + col;
; #pragma unroll
;                 for (int r = 0; r < 16; ++r) { const int io = (r & 3) + 8 * (r >> 2);
;                     if (ch > 0 || 32 * ib + 4 * hi + io >= 48) dst0[(size_t)io * ostride] = (bf16_t)f2bf(acc[r]); }
;             }
;             __syncthreads();
.LBB0_853:
	s_or_b64 exec, exec, s[2:3]
	s_waitcnt lgkmcnt(0)
	s_barrier
	s_nop 0
	s_nop 0
	s_nop 0
	s_nop 0

; #define LAS __attribute__((address_space(3)))
; __device__ __forceinline__ void gla_prep_phase(const Ctx& c, int j, LAS unsigned char* lds) {
;     ...
;         float up[16];
; #pragma unroll
;         for (int r = 0; r < 16; ++r) up[r] = pup[r];
;         const float bias = pbias;
;         { const int un = u + c.G; have = un < 2 * 16 * NCH; if (have) PREP_FETCH(un); }
;         __syncthreads();
;         float run = 0.f;
; #pragma unroll 4
;         for (int ii = 0; ii < 32; ++ii) { const int i = half * 32 + ii; float z = bias;
; #pragma unroll
;             for (int r = 0; r < 16; r += 4) { const f32x4 l4 = *(const LAS f32x4*)(LR + i * 16 + r); z += l4.x * up[r] + l4.y * up[r + 1] + l4.z * up[r + 2] + l4.w * up[r + 3]; }
;             const float ls = fminf(z, 0.f) - __logf(1.f + __expf(-fabsf(z)));
;             const bool valid = (ch > 0) || (i >= 48);
;             run += valid ? ls * (1.f / 16.f) : 0.f; CUM[i * 256 + d] = run; }
.LBB0_1628:
	s_cmp_gt_i32 s95, 0
	s_mov_b32 s0, 0
	v_mov_b32_e32 v152, 0
	s_cselect_b64 s[66:67], -1, 0
	v_mov_b32_e32 v150, v135
	v_mov_b32_e32 v151, v134
	v_mov_b32_e32 v202, v2
	v_mov_b32_e32 v203, v0
	v_mov_b32_e32 v204, v4
	v_mov_b32_e32 v205, v6
	v_mov_b32_e32 v206, v3
	v_mov_b32_e32 v207, v1
	v_mov_b32_e32 v208, v5
	v_mov_b32_e32 v209, v7
	v_mov_b32_e32 v210, v10
	v_mov_b32_e32 v211, v8
	v_mov_b32_e32 v212, v12
	v_mov_b32_e32 v213, v14
	v_mov_b32_e32 v214, v11
	v_mov_b32_e32 v215, v9
	v_mov_b32_e32 v216, v13
	v_mov_b32_e32 v217, v15
	s_waitcnt lgkmcnt(0)
	s_barrier
.LBB0_1629:
	v_add_u32_e32 v173, 0, v150
	ds_read_b128 v[154:157], v173
	ds_read_b128 v[158:161], v173 offset:16
	ds_read_b128 v[162:165], v173 offset:32
	ds_read_b128 v[166:169], v173 offset:48
	v_add_u32_e32 v172, s0, v53
	v_add_u32_e32 v171, 0, v151
	v_add_u32_e32 v174, 2, v172
	s_add_i32 s0, s0, 4
	s_waitcnt lgkmcnt(0)
	v_pk_mul_f32 v[218:219], v[202:203], v[154:155]
	v_pk_mul_f32 v[220:221], v[210:211], v[162:163]
	v_pk_fma_f32 v[218:219], v[204:205], v[156:157], v[218:219]
	v_pk_fma_f32 v[220:221], v[212:213], v[164:165], v[220:221]
	v_pk_fma_f32 v[218:219], v[206:207], v[158:159], v[218:219]
	v_pk_fma_f32 v[220:221], v[214:215], v[166:167], v[220:221]
	v_pk_fma_f32 v[218:219], v[208:209], v[160:161], v[218:219]
	v_pk_fma_f32 v[220:221], v[216:217], v[168:169], v[220:221]
	s_nop 0
	v_pk_add_f32 v[218:219], v[218:219], v[220:221]
	s_nop 0
	v_add_f32_e32 v153, v105, v218
	v_add_f32_e32 v153, v153, v219
	v_min_f32_e32 v154, 0, v153
	v_mul_f32_e64 v153, |v153|, s88
	v_exp_f32_e32 v153, v153
	v_add_u32_e32 v151, 0x1000, v151
	v_add_u32_e32 v150, 0x100, v150
	v_add_f32_e32 v153, 1.0, v153
	v_log_f32_e32 v153, v153
	s_nop 0
	v_mul_f32_e32 v155, 0x3f317217, v153
	v_fma_f32 v155, v153, s90, -v155
	v_fmac_f32_e32 v155, 0x3377d1cf, v153
	v_fmac_f32_e32 v155, 0x3f317217, v153
	v_sub_f32_e32 v153, v154, v155
	v_cmp_lt_i32_e32 vcc, 47, v172
	s_or_b64 vcc, s[66:67], vcc
	v_mul_f32_e32 v153, 0x3d800000, v153
	v_cndmask_b32_e32 v153, 0, v153, vcc
	v_add_f32_e32 v170, v152, v153
	v_add_u32_e32 v152, 0x12000, v171
	ds_write_b32 v152, v170
	ds_read_b128 v[152:155], v173 offset:64
	ds_read_b128 v[156:159], v173 offset:80
	ds_read_b128 v[160:163], v173 offset:96
	ds_read_b128 v[164:167], v173 offset:112
	s_waitcnt lgkmcnt(0)
	v_pk_mul_f32 v[218:219], v[202:203], v[152:153]
	v_pk_mul_f32 v[220:221], v[210:211], v[160:161]
	v_pk_fma_f32 v[218:219], v[204:205], v[154:155], v[218:219]
	v_pk_fma_f32 v[220:221], v[212:213], v[162:163], v[220:221]
	v_pk_fma_f32 v[218:219], v[206:207], v[156:157], v[218:219]
	v_pk_fma_f32 v[220:221], v[214:215], v[164:165], v[220:221]
	v_pk_fma_f32 v[218:219], v[208:209], v[158:159], v[218:219]
	v_pk_fma_f32 v[220:221], v[216:217], v[166:167], v[220:221]
	s_nop 0
	v_pk_add_f32 v[218:219], v[218:219], v[220:221]
	s_nop 0
	v_add_f32_e32 v152, v105, v218
	v_add_f32_e32 v152, v152, v219
	v_min_f32_e32 v153, 0, v152
	v_mul_f32_e64 v152, |v152|, s88
	v_exp_f32_e32 v152, v152
	s_nop 0
	v_add_f32_e32 v152, 1.0, v152
	v_log_f32_e32 v152, v152
	s_nop 0
	v_mul_f32_e32 v154, 0x3f317217, v152
	v_fma_f32 v154, v152, s90, -v154
	v_fmac_f32_e32 v154, 0x3377d1cf, v152
	v_fmac_f32_e32 v154, 0x3f317217, v152
	v_sub_f32_e32 v152, v153, v154
	v_cmp_lt_i32_e32 vcc, 46, v172
	s_or_b64 vcc, s[66:67], vcc
	v_mul_f32_e32 v152, 0x3d800000, v152
	v_cndmask_b32_e32 v152, 0, v152, vcc
	v_add_f32_e32 v170, v170, v152
	v_add_u32_e32 v152, 0x12400, v171
	ds_write_b32 v152, v170
	ds_read_b128 v[152:155], v173 offset:128
	ds_read_b128 v[156:159], v173 offset:144
	ds_read_b128 v[160:163], v173 offset:160
	ds_read_b128 v[164:167], v173 offset:176
	v_add_u32_e32 v172, 3, v172
	s_waitcnt lgkmcnt(0)
	v_pk_mul_f32 v[218:219], v[202:203], v[152:153]
	v_pk_mul_f32 v[220:221], v[210:211], v[160:161]
	v_pk_fma_f32 v[218:219], v[204:205], v[154:155], v[218:219]
	v_pk_fma_f32 v[220:221], v[212:213], v[162:163], v[220:221]
	v_pk_fma_f32 v[218:219], v[206:207], v[156:157], v[218:219]
	v_pk_fma_f32 v[220:221], v[214:215], v[164:165], v[220:221]
	v_pk_fma_f32 v[218:219], v[208:209], v[158:159], v[218:219]
	v_pk_fma_f32 v[220:221], v[216:217], v[166:167], v[220:221]
	s_nop 0
	v_pk_add_f32 v[218:219], v[218:219], v[220:221]
	s_nop 0
	v_add_f32_e32 v152, v105, v218
	v_add_f32_e32 v152, v152, v219
	v_min_f32_e32 v153, 0, v152
	v_mul_f32_e64 v152, |v152|, s88
	v_exp_f32_e32 v152, v152
	s_nop 0
	v_add_f32_e32 v152, 1.0, v152
	v_log_f32_e32 v152, v152
	s_nop 0
	v_mul_f32_e32 v154, 0x3f317217, v152
	v_fma_f32 v154, v152, s90, -v154
	v_fmac_f32_e32 v154, 0x3377d1cf, v152
	v_fmac_f32_e32 v154, 0x3f317217, v152
	v_sub_f32_e32 v152, v153, v154
	v_cmp_lt_i32_e32 vcc, 47, v174
	s_or_b64 vcc, s[66:67], vcc
	v_mul_f32_e32 v152, 0x3d800000, v152
	v_cndmask_b32_e32 v152, 0, v152, vcc
	v_add_f32_e32 v170, v170, v152
	v_add_u32_e32 v152, 0x12800, v171
	ds_write_b32 v152, v170
	ds_read_b128 v[152:155], v173 offset:192
	ds_read_b128 v[156:159], v173 offset:208
	ds_read_b128 v[160:163], v173 offset:224
	ds_read_b128 v[164:167], v173 offset:240
	s_waitcnt lgkmcnt(0)
	v_pk_mul_f32 v[218:219], v[202:203], v[152:153]
	v_pk_mul_f32 v[220:221], v[210:211], v[160:161]
	v_pk_fma_f32 v[218:219], v[204:205], v[154:155], v[218:219]
	v_pk_fma_f32 v[220:221], v[212:213], v[162:163], v[220:221]
	v_pk_fma_f32 v[218:219], v[206:207], v[156:157], v[218:219]
	v_pk_fma_f32 v[220:221], v[214:215], v[164:165], v[220:221]
	v_pk_fma_f32 v[218:219], v[208:209], v[158:159], v[218:219]
	v_pk_fma_f32 v[220:221], v[216:217], v[166:167], v[220:221]
	s_nop 0
	v_pk_add_f32 v[218:219], v[218:219], v[220:221]
	s_nop 0
	v_add_f32_e32 v152, v105, v218
	v_add_f32_e32 v152, v152, v219
	v_min_f32_e32 v153, 0, v152
	v_mul_f32_e64 v152, |v152|, s88
	v_exp_f32_e32 v152, v152
	s_nop 0
	v_add_f32_e32 v152, 1.0, v152
	v_log_f32_e32 v152, v152
	s_nop 0
	v_mul_f32_e32 v154, 0x3f317217, v152
	v_fma_f32 v154, v152, s90, -v154
	v_fmac_f32_e32 v154, 0x3377d1cf, v152
	v_fmac_f32_e32 v154, 0x3f317217, v152
	v_sub_f32_e32 v152, v153, v154
	v_cmp_lt_i32_e32 vcc, 47, v172
	s_or_b64 vcc, s[66:67], vcc
	v_mul_f32_e32 v152, 0x3d800000, v152
	v_cndmask_b32_e32 v152, 0, v152, vcc
	v_add_f32_e32 v152, v170, v152
	v_add_u32_e32 v153, 0x12c00, v171
	s_cmp_eq_u32 s0, 32
	ds_write_b32 v153, v152
	s_cbranch_scc0 .LBB0_1629
; __device__ __forceinline__ unsigned cvt_pk_bf16(float lo, float hi) { unsigned r; asm volatile("v_cvt_pk_bf16_f32 %0, %1, %2" : "=v"(r) : "v"(lo), "v"(hi)); return r; }
; #define LAS __attribute__((address_space(3)))
; __device__ __forceinline__ void gla_prep_phase(const Ctx& c, int j, LAS unsigned char* lds) {
;     ...
;         TOT[half * 256 + d] = run;
;         __syncthreads();
;         const size_t tile = (size_t)(dir * 16 + bh) * NCH + ch;
;         bf16_t* qdst = QD + tile * (64 * 256);
;         {
;             const int dq = (c.tid & 63) * 4, i0 = (c.tid >> 6) * 8, hf = i0 >> 5;
;             const f32x4 t0 = *(const LAS f32x4*)(TOT + dq), t1 = *(const LAS f32x4*)(TOT + 256 + dq), total = t0 + t1;
;             const f32x4 off0 = hf ? t0 : (f32x4){0.f, 0.f, 0.f, 0.f}, sbase = hf ? t1 : total;
;             f32x4 etot; etot.x = __expf(total.x); etot.y = __expf(total.y); etot.z = __expf(total.z); etot.w = __expf(total.w);
;             f32x4 prev = (i0 & 31) ? *(const LAS f32x4*)(CUM + (i0 - 1) * 256 + dq) : (f32x4){0.f, 0.f, 0.f, 0.f};
;             float kf[4][8];
; #pragma unroll
;             for (int e = 0; e < 8; ++e) { const int i = i0 + e;
;                 const f32x4 incl = *(const LAS f32x4*)(CUM + i * 256 + dq);
;                 const f32x4 cum = (dir == 0) ? (off0 + incl) : (sbase - prev); prev = incl;
;                 const u32x2 qw = *(const LAS u32x2*)(QL + i * 528 + dq * 2), kw = *(const LAS u32x2*)(KL + i * 528 + dq * 2);
;                 const float qv[4] = {__uint_as_float(qw.x << 16), __uint_as_float(qw.x & 0xffff0000u), __uint_as_float(qw.y << 16), __uint_as_float(qw.y & 0xffff0000u)};
;                 const float kv[4] = {__uint_as_float(kw.x << 16), __uint_as_float(kw.x & 0xffff0000u), __uint_as_float(kw.y << 16), __uint_as_float(kw.y & 0xffff0000u)};
;                 float qd[4], ki[4];
; #pragma unroll
;                 for (int jx = 0; jx < 4; ++jx) { const float ec = __expf(cum[jx]), rc = __builtin_amdgcn_rcpf(ec);
;                     qd[jx] = qv[jx] * ec * (1.f / 16.f); ki[jx] = kv[jx] * rc; kf[jx][e] = ki[jx] * etot[jx]; }
;                 *(LAS u32x2*)(QL + i * 528 + dq * 2) = (u32x2){pg8::cvt_pk_bf16(qd[0], qd[1]), pg8::cvt_pk_bf16(qd[2], qd[3])};
;                 *(LAS u32x2*)(KL + i * 528 + dq * 2) = (u32x2){pg8::cvt_pk_bf16(ki[0], ki[1]), pg8::cvt_pk_bf16(ki[2], ki[3])}; }
	ds_write_b32 v91, v152 offset:4096
	s_waitcnt lgkmcnt(0)
	s_barrier
	ds_read_b128 v[0:3], v128 offset:4096
	ds_read_b128 v[8:11], v128 offset:5120
	v_mov_b32_e32 v4, 0
	v_mov_b32_e32 v5, 0
	v_mov_b32_e32 v6, 0
	v_mov_b32_e32 v7, 0
	s_and_saveexec_b64 s[0:1], s[38:39]
	ds_read_b128 v[4:7], v132
	s_or_b64 exec, exec, s[0:1]
	s_waitcnt lgkmcnt(0)
	v_pk_add_f32 v[150:151], v[0:1], v[8:9]
	s_lshl_b32 s0, s94, 4
	v_pk_add_f32 v[154:155], v[2:3], v[10:11]
	v_cndmask_b32_e64 v14, v9, v151, s[36:37]
	v_cndmask_b32_e64 v9, v3, 0, s[36:37]
	v_add_u32_e32 v3, v130, v129
	s_add_i32 s0, s0, s96
	v_cndmask_b32_e64 v12, v11, v155, s[36:37]
	v_cndmask_b32_e64 v13, v10, v154, s[36:37]
	v_cndmask_b32_e64 v15, v8, v150, s[36:37]
	v_cndmask_b32_e64 v11, v1, 0, s[36:37]
	v_cndmask_b32_e64 v10, v0, 0, s[36:37]
	v_mul_f32_e32 v0, 0x3fb8aa3b, v150
	v_mul_f32_e32 v1, 0x3fb8aa3b, v151
	ds_read_b128 v[150:153], v3
	s_mul_hi_i32 s1, s0, 0x41
	s_mulk_i32 s0, 0x41
	s_ashr_i32 s33, s95, 31
	s_add_u32 s66, s0, s95
	s_addc_u32 s67, s1, s33
	s_add_i32 s0, s93, 0x40f
	s_cmpk_lt_u32 s0, 0x81f
	v_cndmask_b32_e64 v8, v2, 0, s[36:37]
	v_mul_f32_e32 v2, 0x3fb8aa3b, v154
	v_mul_f32_e32 v3, 0x3fb8aa3b, v155
	s_waitcnt lgkmcnt(0)
	v_pk_add_f32 v[154:155], v[10:11], v[150:151]
	v_sub_f32_e32 v159, v15, v4
	v_sub_f32_e32 v160, v14, v5
	s_cselect_b64 s[54:55], -1, 0
	v_sub_f32_e32 v105, v13, v6
	v_sub_f32_e32 v158, v12, v7
	ds_read2st64_b64 v[4:7], v138 offset0:12 offset1:78
	v_cndmask_b32_e64 v155, v160, v155, s[54:55]
	v_cndmask_b32_e64 v154, v159, v154, s[54:55]
	v_mul_f32_e32 v154, 0x3fb8aa3b, v154
	v_mul_f32_e32 v155, 0x3fb8aa3b, v155
	v_exp_f32_e32 v154, v154
	v_exp_f32_e32 v155, v155
	v_pk_add_f32 v[156:157], v[8:9], v[152:153]
	s_waitcnt lgkmcnt(0)
	v_lshlrev_b32_e32 v159, 16, v6
	v_cndmask_b32_e64 v157, v158, v157, s[54:55]
	v_cndmask_b32_e64 v105, v105, v156, s[54:55]
	v_lshlrev_b32_e32 v156, 16, v4
	v_and_b32_e32 v4, 0xffff0000, v4
	v_rcp_f32_e32 v161, v154
	v_mul_f32_e32 v154, v154, v156
	v_rcp_f32_e32 v156, v155
	v_mul_f32_e32 v4, v155, v4
	v_mul_f32_e32 v105, 0x3fb8aa3b, v105
	v_mul_f32_e32 v155, 0x3fb8aa3b, v157
	v_exp_f32_e32 v105, v105
	v_exp_f32_e32 v155, v155
	v_and_b32_e32 v6, 0xffff0000, v6
	v_lshlrev_b32_e32 v158, 16, v5
	v_and_b32_e32 v5, 0xffff0000, v5
	v_mul_f32_e32 v6, v156, v6
	v_rcp_f32_e32 v156, v105
	v_rcp_f32_e32 v157, v155
	v_mul_f32_e32 v5, v155, v5
	v_mul_f32_e32 v4, 0x3d800000, v4
	v_mul_f32_e32 v105, v105, v158
	v_mul_f32_e32 v5, 0x3d800000, v5
	v_lshlrev_b32_e32 v160, 16, v7
	v_and_b32_e32 v7, 0xffff0000, v7
	v_mul_f32_e32 v154, 0x3d800000, v154
	v_mul_f32_e32 v105, 0x3d800000, v105
	v_cvt_pk_bf16_f32 v4, v154, v4
	v_cvt_pk_bf16_f32 v5, v105, v5
	v_mul_f32_e32 v159, v161, v159
	v_mul_f32_e32 v158, v156, v160
	v_mul_f32_e32 v160, v157, v7
	ds_write_b64 v138, v[4:5] offset:6144
	v_cvt_pk_bf16_f32 v4, v159, v6
	v_cvt_pk_bf16_f32 v5, v158, v160
	ds_write_b64 v138, v[4:5] offset:39936
	ds_read_b128 v[154:157], v139
	v_exp_f32_e32 v0, v0
	v_exp_f32_e32 v2, v2
	v_sub_f32_e32 v105, v15, v150
	v_sub_f32_e32 v162, v14, v151
	v_mul_f32_e32 v7, v0, v159
	v_mul_f32_e32 v5, v2, v158
	s_waitcnt lgkmcnt(0)
	v_pk_add_f32 v[158:159], v[10:11], v[154:155]
	v_add_u32_e32 v150, 16, v138
	v_cndmask_b32_e64 v105, v105, v158, s[54:55]
	v_mul_f32_e32 v105, 0x3fb8aa3b, v105
	v_exp_f32_e32 v105, v105
	v_exp_f32_e32 v3, v3
	v_sub_f32_e32 v163, v13, v152
	v_sub_f32_e32 v164, v12, v153
	ds_read2st64_b64 v[150:153], v150 offset0:13 offset1:79
	v_cndmask_b32_e64 v159, v162, v159, s[54:55]
	v_mul_f32_e32 v159, 0x3fb8aa3b, v159
	v_rcp_f32_e32 v165, v105
	v_exp_f32_e32 v159, v159
	v_mul_f32_e32 v4, v3, v160
	v_pk_add_f32 v[160:161], v[8:9], v[156:157]
	s_waitcnt lgkmcnt(0)
	v_lshlrev_b32_e32 v158, 16, v150
	v_cndmask_b32_e64 v160, v163, v160, s[54:55]
	v_lshlrev_b32_e32 v163, 16, v152
	v_mul_f32_e32 v105, v105, v158
	v_mul_f32_e32 v158, v165, v163
	v_rcp_f32_e32 v163, v159
	v_cndmask_b32_e64 v161, v164, v161, s[54:55]
	v_and_b32_e32 v150, 0xffff0000, v150
	v_and_b32_e32 v152, 0xffff0000, v152
	v_mul_f32_e32 v150, v159, v150
	v_mul_f32_e32 v159, 0x3fb8aa3b, v160
	v_mul_f32_e32 v160, v163, v152
	v_mul_f32_e32 v152, 0x3fb8aa3b, v161
	v_exp_f32_e32 v159, v159
	v_exp_f32_e32 v152, v152
	v_lshlrev_b32_e32 v162, 16, v151
	v_and_b32_e32 v151, 0xffff0000, v151
	v_rcp_f32_e32 v161, v159
	v_mul_f32_e32 v159, v159, v162
	v_rcp_f32_e32 v162, v152
	v_mul_f32_e32 v151, v152, v151
	v_mul_f32_e32 v150, 0x3d800000, v150
	v_mul_f32_e32 v151, 0x3d800000, v151
	v_lshlrev_b32_e32 v164, 16, v153
	v_and_b32_e32 v153, 0xffff0000, v153
	v_mul_f32_e32 v105, 0x3d800000, v105
	v_mul_f32_e32 v159, 0x3d800000, v159
	v_cvt_pk_bf16_f32 v150, v105, v150
	v_cvt_pk_bf16_f32 v151, v159, v151
	v_mul_f32_e32 v161, v161, v164
	v_mul_f32_e32 v162, v162, v153
	ds_write_b64 v138, v[150:151] offset:6672
	v_cvt_pk_bf16_f32 v150, v158, v160
	v_cvt_pk_bf16_f32 v151, v161, v162
	ds_write_b64 v138, v[150:151] offset:40464
	ds_read_b128 v[150:153], v140
	v_mul_f32_e32 v163, v0, v158
	v_mul_f32_e32 v105, v3, v162
	v_sub_f32_e32 v162, v15, v154
	v_sub_f32_e32 v166, v14, v155
	s_waitcnt lgkmcnt(0)
	v_pk_add_f32 v[158:159], v[10:11], v[150:151]
	v_add_u32_e32 v154, 32, v138
	v_cndmask_b32_e64 v158, v162, v158, s[54:55]
	v_mul_f32_e32 v158, 0x3fb8aa3b, v158
	v_exp_f32_e32 v158, v158
	v_exp_f32_e32 v1, v1
	v_sub_f32_e32 v167, v13, v156
	v_sub_f32_e32 v168, v12, v157
	ds_read2st64_b64 v[154:157], v154 offset0:14 offset1:80
	v_cndmask_b32_e64 v159, v166, v159, s[54:55]
	v_mul_f32_e32 v159, 0x3fb8aa3b, v159
	v_rcp_f32_e32 v169, v158
	v_exp_f32_e32 v159, v159
	v_mul_f32_e32 v164, v1, v160
	v_mul_f32_e32 v165, v2, v161
	v_pk_add_f32 v[160:161], v[8:9], v[152:153]
	s_waitcnt lgkmcnt(0)
; __device__ __forceinline__ unsigned cvt_pk_bf16(float lo, float hi) { unsigned r; asm volatile("v_cvt_pk_bf16_f32 %0, %1, %2" : "=v"(r) : "v"(lo), "v"(hi)); return r; }
; #define LAS __attribute__((address_space(3)))
; __device__ __forceinline__ void gla_prep_phase(const Ctx& c, int j, LAS unsigned char* lds) {
;     ...
;             for (int e = 0; e < 8; ++e) { const int i = i0 + e;
;                 const f32x4 incl = *(const LAS f32x4*)(CUM + i * 256 + dq);
;                 const f32x4 cum = (dir == 0) ? (off0 + incl) : (sbase - prev); prev = incl;
;                 const u32x2 qw = *(const LAS u32x2*)(QL + i * 528 + dq * 2), kw = *(const LAS u32x2*)(KL + i * 528 + dq * 2);
;                 const float qv[4] = {__uint_as_float(qw.x << 16), __uint_as_float(qw.x & 0xffff0000u), __uint_as_float(qw.y << 16), __uint_as_float(qw.y & 0xffff0000u)};
;                 const float kv[4] = {__uint_as_float(kw.x << 16), __uint_as_float(kw.x & 0xffff0000u), __uint_as_float(kw.y << 16), __uint_as_float(kw.y & 0xffff0000u)};
;                 float qd[4], ki[4];
; #pragma unroll
;                 for (int jx = 0; jx < 4; ++jx) { const float ec = __expf(cum[jx]), rc = __builtin_amdgcn_rcpf(ec);
;                     qd[jx] = qv[jx] * ec * (1.f / 16.f); ki[jx] = kv[jx] * rc; kf[jx][e] = ki[jx] * etot[jx]; }
;                 *(LAS u32x2*)(QL + i * 528 + dq * 2) = (u32x2){pg8::cvt_pk_bf16(qd[0], qd[1]), pg8::cvt_pk_bf16(qd[2], qd[3])};
;                 *(LAS u32x2*)(KL + i * 528 + dq * 2) = (u32x2){pg8::cvt_pk_bf16(ki[0], ki[1]), pg8::cvt_pk_bf16(ki[2], ki[3])}; }
	v_lshlrev_b32_e32 v162, 16, v154
	v_cndmask_b32_e64 v160, v167, v160, s[54:55]
	v_lshlrev_b32_e32 v167, 16, v156
	v_mul_f32_e32 v158, v158, v162
	v_mul_f32_e32 v162, v169, v167
	v_rcp_f32_e32 v167, v159
	v_cndmask_b32_e64 v161, v168, v161, s[54:55]
	v_and_b32_e32 v154, 0xffff0000, v154
	v_and_b32_e32 v156, 0xffff0000, v156
	v_mul_f32_e32 v154, v159, v154
	v_mul_f32_e32 v159, 0x3fb8aa3b, v160
	v_mul_f32_e32 v160, v167, v156
	v_mul_f32_e32 v156, 0x3fb8aa3b, v161
	v_exp_f32_e32 v159, v159
	v_exp_f32_e32 v156, v156
	v_lshlrev_b32_e32 v166, 16, v155
	v_and_b32_e32 v155, 0xffff0000, v155
	v_rcp_f32_e32 v161, v159
	v_mul_f32_e32 v159, v159, v166
	v_rcp_f32_e32 v166, v156
	v_mul_f32_e32 v155, v156, v155
	v_mul_f32_e32 v154, 0x3d800000, v154
	v_mul_f32_e32 v155, 0x3d800000, v155
	v_lshlrev_b32_e32 v168, 16, v157
	v_and_b32_e32 v157, 0xffff0000, v157
	v_mul_f32_e32 v158, 0x3d800000, v158
	v_mul_f32_e32 v159, 0x3d800000, v159
	v_cvt_pk_bf16_f32 v154, v158, v154
	v_cvt_pk_bf16_f32 v155, v159, v155
	v_mul_f32_e32 v161, v161, v168
	v_mul_f32_e32 v166, v166, v157
	ds_write_b64 v138, v[154:155] offset:7200
	v_cvt_pk_bf16_f32 v154, v162, v160
	v_cvt_pk_bf16_f32 v155, v161, v166
	ds_write_b64 v138, v[154:155] offset:40992
	ds_read_b128 v[154:157], v141
	v_sub_f32_e32 v169, v15, v150
	v_sub_f32_e32 v170, v14, v151
	v_add_u32_e32 v150, 48, v138
	v_sub_f32_e32 v171, v13, v152
	s_waitcnt lgkmcnt(0)
	v_pk_add_f32 v[158:159], v[10:11], v[154:155]
	v_sub_f32_e32 v172, v12, v153
	v_cndmask_b32_e64 v158, v169, v158, s[54:55]
	v_mul_f32_e32 v158, 0x3fb8aa3b, v158
	v_exp_f32_e32 v158, v158
	ds_read2st64_b64 v[150:153], v150 offset0:15 offset1:81
	v_cndmask_b32_e64 v159, v170, v159, s[54:55]
	v_mul_f32_e32 v159, 0x3fb8aa3b, v159
	v_rcp_f32_e32 v173, v158
	v_exp_f32_e32 v159, v159
	v_mul_f32_e32 v167, v1, v160
	v_mul_f32_e32 v168, v2, v161
	v_pk_add_f32 v[160:161], v[8:9], v[156:157]
	s_waitcnt lgkmcnt(0)
	v_lshlrev_b32_e32 v169, 16, v150
	v_cndmask_b32_e64 v160, v171, v160, s[54:55]
	v_lshlrev_b32_e32 v171, 16, v152
	v_mul_f32_e32 v158, v158, v169
	v_mul_f32_e32 v169, v173, v171
	v_rcp_f32_e32 v171, v159
	v_cndmask_b32_e64 v161, v172, v161, s[54:55]
	v_and_b32_e32 v150, 0xffff0000, v150
	v_and_b32_e32 v152, 0xffff0000, v152
	v_mul_f32_e32 v150, v159, v150
	v_mul_f32_e32 v159, 0x3fb8aa3b, v160
	v_mul_f32_e32 v160, v171, v152
	v_mul_f32_e32 v152, 0x3fb8aa3b, v161
	v_exp_f32_e32 v159, v159
	v_exp_f32_e32 v152, v152
	v_lshlrev_b32_e32 v170, 16, v151
	v_and_b32_e32 v151, 0xffff0000, v151
	v_rcp_f32_e32 v161, v159
	v_mul_f32_e32 v159, v159, v170
	v_rcp_f32_e32 v170, v152
	v_mul_f32_e32 v151, v152, v151
	v_mul_f32_e32 v150, 0x3d800000, v150
	v_mul_f32_e32 v151, 0x3d800000, v151
	v_lshlrev_b32_e32 v172, 16, v153
	v_and_b32_e32 v153, 0xffff0000, v153
	v_mul_f32_e32 v158, 0x3d800000, v158
	v_mul_f32_e32 v159, 0x3d800000, v159
	v_cvt_pk_bf16_f32 v150, v158, v150
	v_cvt_pk_bf16_f32 v151, v159, v151
	v_mul_f32_e32 v161, v161, v172
	v_mul_f32_e32 v170, v170, v153
	ds_write_b64 v138, v[150:151] offset:7728
	v_cvt_pk_bf16_f32 v150, v169, v160
	v_cvt_pk_bf16_f32 v151, v161, v170
	ds_write_b64 v138, v[150:151] offset:41520
	ds_read_b128 v[150:153], v142
	v_sub_f32_e32 v173, v15, v154
	v_sub_f32_e32 v174, v14, v155
	v_add_u32_e32 v154, 64, v138
	v_sub_f32_e32 v175, v13, v156
	s_waitcnt lgkmcnt(0)
	v_pk_add_f32 v[158:159], v[10:11], v[150:151]
	v_sub_f32_e32 v176, v12, v157
	v_cndmask_b32_e64 v158, v173, v158, s[54:55]
	v_mul_f32_e32 v158, 0x3fb8aa3b, v158
	v_exp_f32_e32 v158, v158
	ds_read2st64_b64 v[154:157], v154 offset0:16 offset1:82
	v_cndmask_b32_e64 v159, v174, v159, s[54:55]
	v_mul_f32_e32 v159, 0x3fb8aa3b, v159
	v_rcp_f32_e32 v177, v158
	v_exp_f32_e32 v159, v159
	v_mul_f32_e32 v171, v1, v160
	v_mul_f32_e32 v172, v2, v161
	v_pk_add_f32 v[160:161], v[8:9], v[152:153]
	s_waitcnt lgkmcnt(0)
	v_lshlrev_b32_e32 v173, 16, v154
	v_cndmask_b32_e64 v160, v175, v160, s[54:55]
	v_lshlrev_b32_e32 v175, 16, v156
	v_mul_f32_e32 v158, v158, v173
	v_mul_f32_e32 v173, v177, v175
	v_rcp_f32_e32 v175, v159
	v_cndmask_b32_e64 v161, v176, v161, s[54:55]
	v_and_b32_e32 v154, 0xffff0000, v154
	v_and_b32_e32 v156, 0xffff0000, v156
	v_mul_f32_e32 v154, v159, v154
	v_mul_f32_e32 v159, 0x3fb8aa3b, v160
	v_mul_f32_e32 v160, v175, v156
	v_mul_f32_e32 v156, 0x3fb8aa3b, v161
	v_exp_f32_e32 v159, v159
	v_exp_f32_e32 v156, v156
	v_lshlrev_b32_e32 v174, 16, v155
	v_and_b32_e32 v155, 0xffff0000, v155
	v_rcp_f32_e32 v161, v159
	v_mul_f32_e32 v159, v159, v174
	v_rcp_f32_e32 v174, v156
	v_mul_f32_e32 v155, v156, v155
	v_mul_f32_e32 v154, 0x3d800000, v154
	v_mul_f32_e32 v155, 0x3d800000, v155
	v_lshlrev_b32_e32 v176, 16, v157
	v_and_b32_e32 v157, 0xffff0000, v157
	v_mul_f32_e32 v158, 0x3d800000, v158
	v_mul_f32_e32 v159, 0x3d800000, v159
	v_cvt_pk_bf16_f32 v154, v158, v154
	v_cvt_pk_bf16_f32 v155, v159, v155
	v_mul_f32_e32 v161, v161, v176
	v_mul_f32_e32 v174, v174, v157
	ds_write_b64 v138, v[154:155] offset:8256
	v_cvt_pk_bf16_f32 v154, v173, v160
	v_cvt_pk_bf16_f32 v155, v161, v174
	ds_write_b64 v138, v[154:155] offset:42048
	ds_read_b128 v[154:157], v143
	v_sub_f32_e32 v177, v15, v150
	v_sub_f32_e32 v178, v14, v151
	v_add_u32_e32 v150, 0x50, v138
	v_sub_f32_e32 v179, v13, v152
	s_waitcnt lgkmcnt(0)
	v_pk_add_f32 v[158:159], v[10:11], v[154:155]
	v_sub_f32_e32 v180, v12, v153
	v_cndmask_b32_e64 v158, v177, v158, s[54:55]
	v_mul_f32_e32 v158, 0x3fb8aa3b, v158
	v_exp_f32_e32 v158, v158
	ds_read2st64_b64 v[150:153], v150 offset0:17 offset1:83
	v_cndmask_b32_e64 v159, v178, v159, s[54:55]
	v_mul_f32_e32 v159, 0x3fb8aa3b, v159
	v_rcp_f32_e32 v181, v158
	v_exp_f32_e32 v159, v159
	v_mul_f32_e32 v175, v1, v160
	v_mul_f32_e32 v176, v2, v161
	v_pk_add_f32 v[160:161], v[8:9], v[156:157]
	s_waitcnt lgkmcnt(0)
; __device__ __forceinline__ unsigned cvt_pk_bf16(float lo, float hi) { unsigned r; asm volatile("v_cvt_pk_bf16_f32 %0, %1, %2" : "=v"(r) : "v"(lo), "v"(hi)); return r; }
; #define LAS __attribute__((address_space(3)))
; __device__ __forceinline__ void gla_prep_phase(const Ctx& c, int j, LAS unsigned char* lds) {
;     ...
;             for (int e = 0; e < 8; ++e) { const int i = i0 + e;
;                 const f32x4 incl = *(const LAS f32x4*)(CUM + i * 256 + dq);
;                 const f32x4 cum = (dir == 0) ? (off0 + incl) : (sbase - prev); prev = incl;
;                 const u32x2 qw = *(const LAS u32x2*)(QL + i * 528 + dq * 2), kw = *(const LAS u32x2*)(KL + i * 528 + dq * 2);
;                 const float qv[4] = {__uint_as_float(qw.x << 16), __uint_as_float(qw.x & 0xffff0000u), __uint_as_float(qw.y << 16), __uint_as_float(qw.y & 0xffff0000u)};
;                 const float kv[4] = {__uint_as_float(kw.x << 16), __uint_as_float(kw.x & 0xffff0000u), __uint_as_float(kw.y << 16), __uint_as_float(kw.y & 0xffff0000u)};
;                 float qd[4], ki[4];
; #pragma unroll
;                 for (int jx = 0; jx < 4; ++jx) { const float ec = __expf(cum[jx]), rc = __builtin_amdgcn_rcpf(ec);
;                     qd[jx] = qv[jx] * ec * (1.f / 16.f); ki[jx] = kv[jx] * rc; kf[jx][e] = ki[jx] * etot[jx]; }
;                 *(LAS u32x2*)(QL + i * 528 + dq * 2) = (u32x2){pg8::cvt_pk_bf16(qd[0], qd[1]), pg8::cvt_pk_bf16(qd[2], qd[3])};
;                 *(LAS u32x2*)(KL + i * 528 + dq * 2) = (u32x2){pg8::cvt_pk_bf16(ki[0], ki[1]), pg8::cvt_pk_bf16(ki[2], ki[3])}; }
;             bf16_t* kdst = KET + tile * (256 * 64) + (size_t)dq * 64 + i0;
; #pragma unroll
;             for (int jx = 0; jx < 4; ++jx)
;                 *(u32x4*)(kdst + jx * 64) = (u32x4){pg8::cvt_pk_bf16(kf[jx][0], kf[jx][1]), pg8::cvt_pk_bf16(kf[jx][2], kf[jx][3]), pg8::cvt_pk_bf16(kf[jx][4], kf[jx][5]), pg8::cvt_pk_bf16(kf[jx][6], kf[jx][7])};
;             if (i0 == 0) *(f32x4*)(DEC + tile * 256 + dq) = etot;
	v_lshlrev_b32_e32 v177, 16, v150
	v_cndmask_b32_e64 v160, v179, v160, s[54:55]
	v_lshlrev_b32_e32 v179, 16, v152
	v_mul_f32_e32 v158, v158, v177
	v_mul_f32_e32 v177, v181, v179
	v_rcp_f32_e32 v179, v159
	v_cndmask_b32_e64 v161, v180, v161, s[54:55]
	v_and_b32_e32 v150, 0xffff0000, v150
	v_and_b32_e32 v152, 0xffff0000, v152
	v_mul_f32_e32 v150, v159, v150
	v_mul_f32_e32 v159, 0x3fb8aa3b, v160
	v_mul_f32_e32 v160, v179, v152
	v_mul_f32_e32 v152, 0x3fb8aa3b, v161
	v_exp_f32_e32 v159, v159
	v_exp_f32_e32 v152, v152
	v_lshlrev_b32_e32 v178, 16, v151
	v_and_b32_e32 v151, 0xffff0000, v151
	v_rcp_f32_e32 v161, v159
	v_mul_f32_e32 v159, v159, v178
	v_rcp_f32_e32 v178, v152
	v_mul_f32_e32 v151, v152, v151
	v_mul_f32_e32 v150, 0x3d800000, v150
	v_mul_f32_e32 v151, 0x3d800000, v151
	v_lshlrev_b32_e32 v180, 16, v153
	v_and_b32_e32 v153, 0xffff0000, v153
	v_mul_f32_e32 v158, 0x3d800000, v158
	v_mul_f32_e32 v159, 0x3d800000, v159
	v_cvt_pk_bf16_f32 v150, v158, v150
	v_cvt_pk_bf16_f32 v151, v159, v151
	v_mul_f32_e32 v161, v161, v180
	v_mul_f32_e32 v178, v178, v153
	ds_write_b64 v138, v[150:151] offset:8784
	v_cvt_pk_bf16_f32 v150, v177, v160
	v_cvt_pk_bf16_f32 v151, v161, v178
	ds_write_b64 v138, v[150:151] offset:42576
	ds_read_b128 v[150:153], v144
	v_sub_f32_e32 v181, v15, v154
	v_sub_f32_e32 v182, v14, v155
	v_add_u32_e32 v154, 0x60, v138
	v_sub_f32_e32 v183, v13, v156
	s_waitcnt lgkmcnt(0)
	v_pk_add_f32 v[158:159], v[10:11], v[150:151]
	v_sub_f32_e32 v184, v12, v157
	v_cndmask_b32_e64 v158, v181, v158, s[54:55]
	v_mul_f32_e32 v158, 0x3fb8aa3b, v158
	v_exp_f32_e32 v158, v158
	ds_read2st64_b64 v[154:157], v154 offset0:18 offset1:84
	v_cndmask_b32_e64 v159, v182, v159, s[54:55]
	v_mul_f32_e32 v159, 0x3fb8aa3b, v159
	v_rcp_f32_e32 v185, v158
	v_exp_f32_e32 v159, v159
	v_mul_f32_e32 v179, v1, v160
	v_mul_f32_e32 v180, v2, v161
	v_pk_add_f32 v[160:161], v[8:9], v[152:153]
	s_waitcnt lgkmcnt(0)
	v_lshlrev_b32_e32 v181, 16, v154
	v_cndmask_b32_e64 v160, v183, v160, s[54:55]
	v_lshlrev_b32_e32 v183, 16, v156
	v_mul_f32_e32 v158, v158, v181
	v_mul_f32_e32 v181, v185, v183
	v_rcp_f32_e32 v183, v159
	v_cndmask_b32_e64 v161, v184, v161, s[54:55]
	v_and_b32_e32 v154, 0xffff0000, v154
	v_and_b32_e32 v156, 0xffff0000, v156
	v_mul_f32_e32 v154, v159, v154
	v_mul_f32_e32 v159, 0x3fb8aa3b, v160
	v_mul_f32_e32 v160, v183, v156
	v_mul_f32_e32 v156, 0x3fb8aa3b, v161
	v_exp_f32_e32 v159, v159
	v_exp_f32_e32 v156, v156
	v_lshlrev_b32_e32 v182, 16, v155
	v_and_b32_e32 v155, 0xffff0000, v155
	v_rcp_f32_e32 v161, v159
	v_mul_f32_e32 v159, v159, v182
	v_rcp_f32_e32 v182, v156
	v_mul_f32_e32 v155, v156, v155
	v_mul_f32_e32 v154, 0x3d800000, v154
	v_mul_f32_e32 v155, 0x3d800000, v155
	v_lshlrev_b32_e32 v184, 16, v157
	v_and_b32_e32 v157, 0xffff0000, v157
	v_mul_f32_e32 v158, 0x3d800000, v158
	v_mul_f32_e32 v159, 0x3d800000, v159
	v_cvt_pk_bf16_f32 v154, v158, v154
	v_cvt_pk_bf16_f32 v155, v159, v155
	v_mul_f32_e32 v161, v161, v184
	v_mul_f32_e32 v182, v182, v157
	ds_write_b64 v138, v[154:155] offset:9312
	v_cvt_pk_bf16_f32 v154, v181, v160
	v_cvt_pk_bf16_f32 v155, v161, v182
	ds_write_b64 v138, v[154:155] offset:43104
	ds_read_b128 v[154:157], v145
	v_sub_f32_e32 v15, v15, v150
	v_sub_f32_e32 v14, v14, v151
	v_sub_f32_e32 v13, v13, v152
	v_sub_f32_e32 v12, v12, v153
	s_waitcnt lgkmcnt(0)
	v_pk_add_f32 v[154:155], v[10:11], v[154:155]
	v_pk_add_f32 v[156:157], v[8:9], v[156:157]
	v_cndmask_b32_e64 v15, v15, v154, s[54:55]
	v_mul_f32_e32 v15, 0x3fb8aa3b, v15
	v_exp_f32_e32 v15, v15
	ds_read2st64_b64 v[8:11], v146 offset0:12 offset1:78
	v_cndmask_b32_e64 v14, v14, v155, s[54:55]
	v_mul_f32_e32 v14, 0x3fb8aa3b, v14
	v_rcp_f32_e32 v154, v15
	v_exp_f32_e32 v14, v14
	v_cndmask_b32_e64 v13, v13, v156, s[54:55]
	s_waitcnt lgkmcnt(0)
	v_lshlrev_b32_e32 v150, 16, v8
	v_lshlrev_b32_e32 v152, 16, v10
	v_mul_f32_e32 v13, 0x3fb8aa3b, v13
	v_mul_f32_e32 v15, v15, v150
	v_mul_f32_e32 v150, v154, v152
	v_rcp_f32_e32 v154, v14
	v_exp_f32_e32 v13, v13
	v_cndmask_b32_e64 v12, v12, v157, s[54:55]
	v_and_b32_e32 v10, 0xffff0000, v10
	v_mul_f32_e32 v12, 0x3fb8aa3b, v12
	v_mul_f32_e32 v10, v154, v10
	v_rcp_f32_e32 v154, v13
	v_exp_f32_e32 v12, v12
	v_lshlrev_b32_e32 v151, 16, v9
	v_lshlrev_b32_e32 v153, 16, v11
	v_and_b32_e32 v8, 0xffff0000, v8
	v_and_b32_e32 v9, 0xffff0000, v9
	v_mul_f32_e32 v13, v13, v151
	v_mul_f32_e32 v151, v154, v153
	v_rcp_f32_e32 v153, v12
	v_mul_f32_e32 v8, v14, v8
	v_mul_f32_e32 v9, v12, v9
	v_mul_f32_e32 v8, 0x3d800000, v8
	v_mul_f32_e32 v9, 0x3d800000, v9
	v_and_b32_e32 v11, 0xffff0000, v11
	v_mul_f32_e32 v15, 0x3d800000, v15
	v_mul_f32_e32 v13, 0x3d800000, v13
	v_cvt_pk_bf16_f32 v8, v15, v8
	v_cvt_pk_bf16_f32 v9, v13, v9
	s_lshl_b64 s[0:1], s[66:67], 15
	v_mul_f32_e32 v6, v1, v6
	v_mul_f32_e32 v11, v153, v11
	ds_write_b64 v146, v[8:9] offset:6144
	v_cvt_pk_bf16_f32 v8, v150, v10
	v_cvt_pk_bf16_f32 v9, v151, v11
	v_lshl_add_u64 v[12:13], v[92:93], 0, s[0:1]
	v_mul_f32_e32 v162, v0, v162
	v_mul_f32_e32 v169, v0, v169
	v_mul_f32_e32 v173, v0, v173
	v_mul_f32_e32 v177, v0, v177
	v_mul_f32_e32 v158, v0, v181
	v_mul_f32_e32 v152, v0, v150
	v_mul_f32_e32 v14, v1, v10
	v_mul_f32_e32 v153, v3, v11
	ds_write_b64 v146, v[8:9] offset:39936
	v_cvt_pk_bf16_f32 v8, v7, v163
	v_cvt_pk_bf16_f32 v9, v162, v169
	v_cvt_pk_bf16_f32 v10, v173, v177
	v_cvt_pk_bf16_f32 v11, v158, v152
	global_store_dwordx4 v[12:13], v[8:11], off
	v_cvt_pk_bf16_f32 v6, v6, v164
	v_cvt_pk_bf16_f32 v7, v167, v171
	v_mul_f32_e32 v159, v1, v160
	v_mul_f32_e32 v166, v3, v166
	v_cvt_pk_bf16_f32 v8, v175, v179
	v_cvt_pk_bf16_f32 v9, v159, v14
	global_store_dwordx4 v[12:13], v[6:9], off offset:128
	v_mul_f32_e32 v170, v3, v170
	v_mul_f32_e32 v174, v3, v174
	v_cvt_pk_bf16_f32 v6, v5, v165
	v_cvt_pk_bf16_f32 v7, v168, v172
	v_mul_f32_e32 v178, v3, v178
	v_mul_f32_e32 v160, v2, v161
	v_mul_f32_e32 v161, v3, v182
	v_mul_f32_e32 v154, v2, v151
	v_cvt_pk_bf16_f32 v8, v176, v180
	v_cvt_pk_bf16_f32 v9, v160, v154
	global_store_dwordx4 v[12:13], v[6:9], off offset:256
	v_cvt_pk_bf16_f32 v4, v4, v105
	v_cvt_pk_bf16_f32 v5, v166, v170
	s_nop 1
	v_cvt_pk_bf16_f32 v6, v174, v178
	v_cvt_pk_bf16_f32 v7, v161, v153
	global_store_dwordx4 v[12:13], v[4:7], off offset:384
	s_and_saveexec_b64 s[0:1], s[52:53]
	s_cbranch_execz .LBB0_1634
	s_lshl_b64 s[58:59], s[66:67], 10
	v_lshl_add_u64 v[4:5], v[94:95], 0, s[58:59]
	global_store_dwordx4 v[4:5], v[0:3], off

; __device__ __forceinline__ unsigned cvt_pk_bf16(float lo, float hi) { unsigned r; asm volatile("v_cvt_pk_bf16_f32 %0, %1, %2" : "=v"(r) : "v"(lo), "v"(hi)); return r; }
; #define LAS __attribute__((address_space(3)))
; __device__ __forceinline__ int crow16(int r, int hi) { return (r & 3) + 8 * (r >> 2) + 4 * hi; }
; __device__ __forceinline__ void gla_prep_phase(const Ctx& c, int j, LAS unsigned char* lds) {
;     ...
;         if (wid < 4) {
;             const int ib = wid & 1, sb = wid >> 1; f32x16 acc = {};
; #pragma unroll 4
;             for (int ks = 0; ks < 16; ++ks) {
;                 const bf16x8 a = *(const LAS bf16x8*)(QL + (32 * ib + r32) * 528 + (ks * 16 + hi * 8) * 2);
;                 const bf16x8 bb = *(const LAS bf16x8*)(KL + (32 * sb + r32) * 528 + (ks * 16 + hi * 8) * 2);
;                 acc = __builtin_amdgcn_mfma_f32_32x32x16_bf16(a, bb, acc, 0, 0, 0); }
;             bf16_t* pdst = PM + tile * (64 * 64);
; #pragma unroll
;             for (int r = 0; r < 16; ++r) { const int i = 32 * ib + crow16(r, hi), s = 32 * sb + r32;
;                 const bool keep = (dir == 0) ? (s <= i) : (s > i);
;                 pdst[i * 64 + s] = (bf16_t)(pg8::cvt_pk_bf16(keep ? acc[r] : 0.f, 0.f) & 0xffffu); }
;         }
;     }
.LBB0_1693:
	s_or_b64 exec, exec, s[2:3]
	s_waitcnt lgkmcnt(0)
	s_barrier
	s_nop 0
	s_nop 0
	s_nop 0
	s_nop 0
	s_nop 0
	s_nop 0
	s_nop 0
	s_nop 0
	s_nop 0
	s_nop 0
	s_nop 0
	s_nop 0
	s_nop 0
	s_nop 0
	s_nop 0
	s_nop 0
	s_nop 0
	s_nop 0
	s_nop 0
	s_nop 0
	s_nop 0
	s_nop 0
	s_nop 0
	s_nop 0
	s_nop 0
	s_nop 0
	s_nop 0
	s_nop 0
	s_nop 0
	s_nop 0
	s_nop 0
	s_nop 0
	s_nop 0
	s_nop 0
	s_nop 0
	s_nop 0
	s_nop 0
	s_nop 0
	s_nop 0
	s_nop 0
	s_nop 0
	s_nop 0
	s_nop 0
	s_nop 0
	s_nop 0
	s_nop 0
	s_nop 0
	s_nop 0
	s_nop 0
	s_nop 0
	s_nop 0
	s_nop 0
	s_nop 0
	s_nop 0
	s_nop 0
	s_nop 0
	s_nop 0
	s_nop 0
	s_nop 0
	s_nop 0
	s_nop 0
	s_nop 0
	s_nop 0
	s_nop 0
	s_nop 0
	s_nop 0
	s_nop 0
	s_nop 0
	s_nop 0
	s_nop 0
	s_nop 0
	s_nop 0
	s_nop 0
	s_nop 0
	s_nop 0
	s_nop 0
	s_nop 0
	s_nop 0
	s_nop 0

; __device__ __forceinline__ unsigned short f2bf(float f) { unsigned u = __float_as_uint(f); return (unsigned short)((u + 0x7fffu + ((u >> 16) & 1u)) >> 16); }
; __device__ __forceinline__ unsigned f2bf(float f) { return pk2(f, 0.f) & 0xffffu; }
; __device__ __forceinline__ void gla_scan_phase(const Ctx& c, LAS unsigned char* lds) {
;     ...
;             if (wid < 4) {
;                 const int ib = wid & 1, eb = wid >> 1;
;                 const int col = h * 512 + es * 64 + 32 * eb + r32;
;                 const int rbase = (ch == 0 ? NREAL + b * NMETA - 48 : b * SEQ + (ch - 1) * 64) + 32 * ib + 4 * hi;
;                 bf16_t* obase = dir == 0 ? Pw : A; const int ostride = dir == 0 ? GLA_NP : DM;
;                 bf16_t* dst0 = obase + (size_t)rbase * ostride + col;
; #pragma unroll
;                 for (int r = 0; r < 16; ++r) { const int io = (r & 3) + 8 * (r >> 2);
;                     if (ch > 0 || 32 * ib + 4 * hi + io >= 48) dst0[(size_t)io * ostride] = (bf16_t)f2bf(acc[r]); }
;             }
;             __syncthreads();
.LBB0_1809:
	s_or_b64 exec, exec, s[2:3]
	s_waitcnt lgkmcnt(0)
	s_barrier
	s_nop 0
	s_nop 0
